# stack11 plus sc1 write-through on the output stores of the attention, conv, S5, LN and SGU phases
# baseline (speedup 1.0000x reference)
.LBB0_1329:
	v_lshlrev_b32_e32 v112, 16, v102
	v_and_b32_e32 v113, 0xffff0000, v102
	v_lshlrev_b32_e32 v124, 16, v103
	v_and_b32_e32 v125, 0xffff0000, v103
	v_lshlrev_b32_e32 v128, 16, v106
	v_pk_mul_f32 v[102:103], v[184:185], v[122:123]
	v_and_b32_e32 v106, 0xffff0000, v106
	v_fma_f32 v103, v14, v128, v103
	v_add_f32_e32 v102, v102, v103
	v_mul_f32_e32 v112, v102, v112
	v_pk_mul_f32 v[102:103], v[186:187], v[114:115]
	v_lshlrev_b32_e32 v129, 16, v107
	v_fma_f32 v103, v15, v106, v103
	v_and_b32_e32 v107, 0xffff0000, v107
	v_add_f32_e32 v102, v102, v103
	v_pk_mul_f32 v[98:99], v[182:183], v[98:99]
	v_mul_f32_e32 v106, v102, v113
	v_pk_mul_f32 v[102:103], v[180:181], v[120:121]
	v_fma_f32 v99, v17, v107, v99
	v_fma_f32 v103, v16, v129, v103
	v_add_f32_e32 v98, v98, v99
	v_lshlrev_b32_e32 v130, 16, v108
	v_add_f32_e32 v102, v102, v103
	v_mul_f32_e32 v103, v98, v125
	v_pk_mul_f32 v[98:99], v[176:177], v[118:119]
	v_lshlrev_b32_e32 v126, 16, v104
	v_fma_f32 v99, v2, v130, v99
	v_add_f32_e32 v98, v98, v99
	v_and_b32_e32 v108, 0xffff0000, v108
	v_mul_f32_e32 v107, v98, v126
	v_pk_mul_f32 v[98:99], v[178:179], v[110:111]
	v_and_b32_e32 v104, 0xffff0000, v104
	v_fma_f32 v99, v3, v108, v99
	v_add_f32_e32 v98, v98, v99
	v_lshlrev_b32_e32 v131, 16, v109
	v_mul_f32_e32 v104, v98, v104
	v_pk_mul_f32 v[98:99], v[172:173], v[116:117]
	v_lshlrev_b32_e32 v127, 16, v105
	v_fma_f32 v99, v4, v131, v99
	v_add_f32_e32 v98, v98, v99
	v_and_b32_e32 v109, 0xffff0000, v109
	v_mul_f32_e32 v108, v98, v127
	v_pk_mul_f32 v[98:99], v[174:175], v[100:101]
	v_and_b32_e32 v105, 0xffff0000, v105
	v_fma_f32 v99, v5, v109, v99
	v_add_f32_e32 v98, v98, v99
	v_mul_f32_e32 v101, v98, v105
	s_add_i32 s10, s10, s12
	v_mul_f32_e32 v102, v102, v124
	v_cvt_pk_bf16_f32 v98, v112, v106
	v_cvt_pk_bf16_f32 v99, v102, v103
	v_cvt_pk_bf16_f32 v100, v107, v104
	v_cvt_pk_bf16_f32 v101, v108, v101
	global_store_dwordx4 v[236:237], v[98:101], off sc1
	s_cmp_ge_i32 s10, s9
	v_lshl_add_u64 v[236:237], v[236:237], 0, s[14:15]
	s_cbranch_scc1 .LBB0_1355

.LBB0_1347:
	s_cmpk_gt_u32 s11, 0xffd
	s_cselect_b64 s[22:23], -1, 0
	s_ashr_i32 s4, s10, 12
	s_ashr_i32 s5, s4, 31
	s_add_i32 s16, s11, 0xfffff002
	s_lshl_b64 s[20:21], s[4:5], 14
	s_lshl_b64 s[6:7], s[16:17], 13
	s_cmpk_lt_u32 s11, 0xffe
	s_waitcnt vmcnt(6)
	v_lshlrev_b32_e32 v247, 16, v158
	v_lshlrev_b32_e32 v246, 16, v150
	v_and_b32_e32 v239, 0xffff0000, v158
	v_and_b32_e32 v238, 0xffff0000, v150
	v_lshlrev_b32_e32 v245, 16, v159
	v_lshlrev_b32_e32 v244, 16, v151
	v_and_b32_e32 v159, 0xffff0000, v159
	v_and_b32_e32 v158, 0xffff0000, v151
	v_lshlrev_b32_e32 v243, 16, v160
	v_lshlrev_b32_e32 v242, 16, v152
	v_and_b32_e32 v151, 0xffff0000, v160
	v_and_b32_e32 v150, 0xffff0000, v152
	v_lshlrev_b32_e32 v241, 16, v161
	v_lshlrev_b32_e32 v240, 16, v153
	v_and_b32_e32 v161, 0xffff0000, v161
	v_and_b32_e32 v160, 0xffff0000, v153
	s_cbranch_scc1 .LBB0_1349
	s_add_u32 s4, s26, s20
	s_addc_u32 s5, s27, s21
	s_add_u32 s4, s4, s6
	s_addc_u32 s5, s5, s7
	v_lshlrev_b32_e32 v152, 2, v1
	v_mov_b32_e32 v250, v246
	v_mov_b32_e32 v251, v238
	v_mov_b32_e32 v252, v244
	v_mov_b32_e32 v253, v158
	global_store_dwordx4 v152, v[250:253], s[4:5] sc1
	s_nop 1
	v_mov_b32_e32 v250, v242
	v_mov_b32_e32 v251, v150
	v_mov_b32_e32 v252, v240
	v_mov_b32_e32 v253, v160
	global_store_dwordx4 v152, v[250:253], s[4:5] offset:16 sc1
.LBB0_1349:
	v_lshlrev_b32_e32 v152, 16, v146
	v_and_b32_e32 v153, 0xffff0000, v146
	v_lshlrev_b32_e32 v163, 16, v147
	v_and_b32_e32 v165, 0xffff0000, v147
	v_lshlrev_b32_e32 v249, 16, v154
	v_pk_mul_f32 v[146:147], v[232:233], v[246:247]
	v_and_b32_e32 v154, 0xffff0000, v154
	v_fma_f32 v147, v86, v249, v147
	v_add_f32_e32 v146, v146, v147
	v_mul_f32_e32 v152, v146, v152
	v_pk_mul_f32 v[146:147], v[234:235], v[238:239]
	v_lshlrev_b32_e32 v250, 16, v155
	v_fma_f32 v147, v87, v154, v147
	v_add_f32_e32 v146, v146, v147
	v_mul_f32_e32 v153, v146, v153
	v_pk_mul_f32 v[146:147], v[228:229], v[244:245]
	v_and_b32_e32 v155, 0xffff0000, v155
	v_fma_f32 v147, v88, v250, v147
	v_add_f32_e32 v146, v146, v147
	v_mul_f32_e32 v154, v146, v163
	v_pk_mul_f32 v[146:147], v[230:231], v[158:159]
	v_lshlrev_b32_e32 v251, 16, v156
	v_fma_f32 v147, v89, v155, v147
	v_add_f32_e32 v146, v146, v147
	v_mul_f32_e32 v155, v146, v165
	v_pk_mul_f32 v[146:147], v[224:225], v[242:243]
	v_lshlrev_b32_e32 v169, 16, v148
	v_fma_f32 v147, v74, v251, v147
	v_add_f32_e32 v146, v146, v147
	v_and_b32_e32 v156, 0xffff0000, v156
	v_mul_f32_e32 v158, v146, v169
	v_pk_mul_f32 v[146:147], v[226:227], v[150:151]
	v_and_b32_e32 v148, 0xffff0000, v148
	v_fma_f32 v147, v75, v156, v147
	v_add_f32_e32 v146, v146, v147
	v_lshlrev_b32_e32 v252, 16, v157
	v_mul_f32_e32 v148, v146, v148
	v_pk_mul_f32 v[146:147], v[220:221], v[240:241]
	v_lshlrev_b32_e32 v171, 16, v149
	v_fma_f32 v147, v76, v252, v147
	v_add_f32_e32 v146, v146, v147
	v_and_b32_e32 v157, 0xffff0000, v157
	v_mul_f32_e32 v150, v146, v171
	v_pk_mul_f32 v[146:147], v[222:223], v[160:161]
	v_and_b32_e32 v149, 0xffff0000, v149
	v_fma_f32 v147, v77, v157, v147
	v_add_f32_e32 v146, v146, v147
	v_mul_f32_e32 v149, v146, v149
	v_cvt_pk_bf16_f32 v146, v152, v153
	v_cvt_pk_bf16_f32 v147, v154, v155
	v_cvt_pk_bf16_f32 v148, v158, v148
	v_cvt_pk_bf16_f32 v149, v150, v149
	global_store_dwordx4 v[236:237], v[146:149], off offset:-3072 sc1
	s_waitcnt vmcnt(5)
	v_lshlrev_b32_e32 v155, 16, v134
	v_lshlrev_b32_e32 v152, 16, v143
	v_and_b32_e32 v147, 0xffff0000, v134
	v_and_b32_e32 v134, 0xffff0000, v143
	v_lshlrev_b32_e32 v151, 16, v136
	v_and_b32_e32 v143, 0xffff0000, v136
	v_cndmask_b32_e64 v136, 0, 1, s[22:23]
	v_lshlrev_b32_e32 v154, 16, v142
	v_and_b32_e32 v146, 0xffff0000, v142
	v_lshlrev_b32_e32 v153, 16, v135
	v_and_b32_e32 v135, 0xffff0000, v135
	v_lshlrev_b32_e32 v150, 16, v144
	v_and_b32_e32 v142, 0xffff0000, v144
	v_lshlrev_b32_e32 v149, 16, v137
	v_lshlrev_b32_e32 v148, 16, v145
	v_and_b32_e32 v137, 0xffff0000, v137
	v_cmp_ne_u32_e64 s[4:5], 1, v136
	s_andn2_b64 vcc, exec, s[22:23]
	v_and_b32_e32 v136, 0xffff0000, v145
	s_cbranch_vccnz .LBB0_1351
	s_add_u32 s11, s26, s20
	s_addc_u32 s13, s27, s21
	s_add_u32 s22, s11, s6
	s_addc_u32 s23, s13, s7
	v_lshlrev_b32_e32 v144, 2, v1
	v_mov_b32_e32 v156, v154
	v_mov_b32_e32 v157, v146
	v_mov_b32_e32 v158, v152
	v_mov_b32_e32 v159, v134
	global_store_dwordx4 v144, v[156:159], s[22:23] offset:2048 sc1
	s_nop 1
	v_mov_b32_e32 v156, v150
	v_mov_b32_e32 v157, v142
	v_mov_b32_e32 v158, v148
	v_mov_b32_e32 v159, v136
	global_store_dwordx4 v144, v[156:159], s[22:23] offset:2064 sc1
.LBB0_1351:
	v_lshlrev_b32_e32 v144, 16, v130
	v_and_b32_e32 v145, 0xffff0000, v130
	v_lshlrev_b32_e32 v156, 16, v131
	v_and_b32_e32 v157, 0xffff0000, v131
	v_lshlrev_b32_e32 v160, 16, v138
	v_pk_mul_f32 v[130:131], v[216:217], v[154:155]
	v_and_b32_e32 v138, 0xffff0000, v138
	v_fma_f32 v131, v62, v160, v131
	v_add_f32_e32 v130, v130, v131
	v_mul_f32_e32 v144, v130, v144
	v_pk_mul_f32 v[130:131], v[218:219], v[146:147]
	v_lshlrev_b32_e32 v161, 16, v139
	v_fma_f32 v131, v63, v138, v131
	v_add_f32_e32 v130, v130, v131
	v_mul_f32_e32 v138, v130, v145
	v_pk_mul_f32 v[130:131], v[212:213], v[152:153]
	v_and_b32_e32 v139, 0xffff0000, v139
	v_fma_f32 v131, v64, v161, v131
	v_add_f32_e32 v130, v130, v131
	v_mul_f32_e32 v145, v130, v156
	v_pk_mul_f32 v[130:131], v[214:215], v[134:135]
	v_lshlrev_b32_e32 v163, 16, v140
	v_fma_f32 v131, v65, v139, v131
	v_add_f32_e32 v130, v130, v131
	v_mul_f32_e32 v134, v130, v157
	v_pk_mul_f32 v[130:131], v[208:209], v[150:151]
	v_lshlrev_b32_e32 v158, 16, v132
	v_fma_f32 v131, v50, v163, v131
	v_add_f32_e32 v130, v130, v131
	v_and_b32_e32 v140, 0xffff0000, v140
	v_mul_f32_e32 v135, v130, v158
	v_pk_mul_f32 v[130:131], v[210:211], v[142:143]
	v_and_b32_e32 v132, 0xffff0000, v132
	v_fma_f32 v131, v51, v140, v131
	v_add_f32_e32 v130, v130, v131
	v_lshlrev_b32_e32 v165, 16, v141
	v_mul_f32_e32 v132, v130, v132
	v_pk_mul_f32 v[130:131], v[204:205], v[148:149]
	v_lshlrev_b32_e32 v159, 16, v133
	v_fma_f32 v131, v52, v165, v131
	v_add_f32_e32 v130, v130, v131
	v_and_b32_e32 v141, 0xffff0000, v141
	v_mul_f32_e32 v139, v130, v159
	v_pk_mul_f32 v[130:131], v[206:207], v[136:137]
	v_and_b32_e32 v133, 0xffff0000, v133
	v_fma_f32 v131, v53, v141, v131
	v_add_f32_e32 v130, v130, v131
	v_mul_f32_e32 v133, v130, v133
	v_cvt_pk_bf16_f32 v130, v144, v138
	v_cvt_pk_bf16_f32 v131, v145, v134
	v_cvt_pk_bf16_f32 v132, v135, v132
	v_cvt_pk_bf16_f32 v133, v139, v133
	global_store_dwordx4 v[236:237], v[130:133], off offset:-2048 sc1
	s_waitcnt vmcnt(4)
	v_lshlrev_b32_e32 v139, 16, v114
	v_lshlrev_b32_e32 v138, 16, v126
	v_and_b32_e32 v131, 0xffff0000, v114
	v_and_b32_e32 v130, 0xffff0000, v126
	v_lshlrev_b32_e32 v137, 16, v115
	v_lshlrev_b32_e32 v136, 16, v127
	v_and_b32_e32 v115, 0xffff0000, v115
	v_and_b32_e32 v114, 0xffff0000, v127
	v_lshlrev_b32_e32 v135, 16, v116
	v_lshlrev_b32_e32 v134, 16, v128
	v_and_b32_e32 v127, 0xffff0000, v116
	v_and_b32_e32 v126, 0xffff0000, v128
	v_lshlrev_b32_e32 v133, 16, v117
	v_lshlrev_b32_e32 v132, 16, v129
	v_and_b32_e32 v117, 0xffff0000, v117
	s_and_b64 vcc, exec, s[4:5]
	v_and_b32_e32 v116, 0xffff0000, v129
	s_cbranch_vccnz .LBB0_1353
	s_add_u32 s11, s26, s20
	s_addc_u32 s13, s27, s21
	s_add_u32 s22, s11, s6
	s_addc_u32 s23, s13, s7
	v_mov_b32_e32 v140, v138
	v_mov_b32_e32 v141, v130
	v_mov_b32_e32 v142, v136
	v_mov_b32_e32 v143, v114
	global_store_dwordx4 v164, v[140:143], s[22:23] sc1
	s_nop 1
	v_mov_b32_e32 v140, v134
	v_mov_b32_e32 v141, v126
	v_mov_b32_e32 v142, v132
	v_mov_b32_e32 v143, v116
	global_store_dwordx4 v164, v[140:143], s[22:23] offset:16 sc1
.LBB0_1353:
	v_lshlrev_b32_e32 v128, 16, v118
	v_and_b32_e32 v129, 0xffff0000, v118
	v_lshlrev_b32_e32 v140, 16, v119
	v_and_b32_e32 v141, 0xffff0000, v119
	v_lshlrev_b32_e32 v144, 16, v122
	v_pk_mul_f32 v[118:119], v[200:201], v[138:139]
	v_and_b32_e32 v122, 0xffff0000, v122
	v_fma_f32 v119, v38, v144, v119
	v_add_f32_e32 v118, v118, v119
	v_mul_f32_e32 v128, v118, v128
	v_pk_mul_f32 v[118:119], v[202:203], v[130:131]
	v_lshlrev_b32_e32 v145, 16, v123
	v_fma_f32 v119, v39, v122, v119
	v_and_b32_e32 v123, 0xffff0000, v123
	v_add_f32_e32 v118, v118, v119
	v_pk_mul_f32 v[114:115], v[198:199], v[114:115]
	v_mul_f32_e32 v122, v118, v129
	v_pk_mul_f32 v[118:119], v[196:197], v[136:137]
	v_fma_f32 v115, v41, v123, v115
	v_fma_f32 v119, v40, v145, v119
	v_add_f32_e32 v114, v114, v115
	v_lshlrev_b32_e32 v146, 16, v124
	v_add_f32_e32 v118, v118, v119
	v_mul_f32_e32 v119, v114, v141
	v_pk_mul_f32 v[114:115], v[192:193], v[134:135]
	v_lshlrev_b32_e32 v142, 16, v120
	v_fma_f32 v115, v26, v146, v115
	v_add_f32_e32 v114, v114, v115
	v_and_b32_e32 v124, 0xffff0000, v124
	v_mul_f32_e32 v123, v114, v142
	v_pk_mul_f32 v[114:115], v[194:195], v[126:127]
	v_and_b32_e32 v120, 0xffff0000, v120
	v_fma_f32 v115, v27, v124, v115
	v_add_f32_e32 v114, v114, v115
	v_lshlrev_b32_e32 v147, 16, v125
	v_mul_f32_e32 v120, v114, v120
	v_pk_mul_f32 v[114:115], v[188:189], v[132:133]
	v_lshlrev_b32_e32 v143, 16, v121
	v_fma_f32 v115, v28, v147, v115
	v_add_f32_e32 v114, v114, v115
	v_and_b32_e32 v125, 0xffff0000, v125
	v_mul_f32_e32 v124, v114, v143
	v_pk_mul_f32 v[114:115], v[190:191], v[116:117]
	v_and_b32_e32 v121, 0xffff0000, v121
	v_fma_f32 v115, v29, v125, v115
	v_add_f32_e32 v114, v114, v115
	v_mul_f32_e32 v117, v114, v121
	v_mul_f32_e32 v118, v118, v140
	v_cvt_pk_bf16_f32 v114, v128, v122
	v_cvt_pk_bf16_f32 v115, v118, v119
	v_cvt_pk_bf16_f32 v116, v123, v120
	v_cvt_pk_bf16_f32 v117, v124, v117
	global_store_dwordx4 v[236:237], v[114:117], off offset:-1024 sc1
	s_waitcnt vmcnt(3)
	v_lshlrev_b32_e32 v123, 16, v98
	v_lshlrev_b32_e32 v122, 16, v110
	v_and_b32_e32 v115, 0xffff0000, v98
	v_and_b32_e32 v114, 0xffff0000, v110
	v_lshlrev_b32_e32 v121, 16, v99
	v_lshlrev_b32_e32 v120, 16, v111
	v_and_b32_e32 v99, 0xffff0000, v99
	v_and_b32_e32 v98, 0xffff0000, v111
	v_lshlrev_b32_e32 v119, 16, v100
	v_lshlrev_b32_e32 v118, 16, v112
	v_and_b32_e32 v111, 0xffff0000, v100
	v_and_b32_e32 v110, 0xffff0000, v112
	v_lshlrev_b32_e32 v117, 16, v101
	v_lshlrev_b32_e32 v116, 16, v113
	v_and_b32_e32 v101, 0xffff0000, v101
	s_and_b64 vcc, exec, s[4:5]
	v_and_b32_e32 v100, 0xffff0000, v113
	s_cbranch_vccnz .LBB0_1329
	s_add_u32 s4, s26, s20
	s_addc_u32 s5, s27, s21
	s_add_u32 s4, s4, s6
	s_addc_u32 s5, s5, s7
	v_mov_b32_e32 v124, v122
	v_mov_b32_e32 v125, v114
	v_mov_b32_e32 v126, v120
	v_mov_b32_e32 v127, v98
	global_store_dwordx4 v162, v[124:127], s[4:5] sc1
	s_nop 1
	v_mov_b32_e32 v124, v118
	v_mov_b32_e32 v125, v110
	v_mov_b32_e32 v126, v116
	v_mov_b32_e32 v127, v100
	global_store_dwordx4 v162, v[124:127], s[4:5] offset:16 sc1
	s_branch .LBB0_1329

.LBB0_1357:
	v_readlane_b32 s52, v254, 58
	v_lshlrev_b32_e32 v98, 2, v1
	v_mov_b32_e32 v99, 0
	v_readlane_b32 s53, v254, 59
	s_load_dwordx16 s[36:51], s[0:1], 0x0
	v_mov_b32_e32 v102, 0x6000
	v_lshl_add_u64 v[100:101], s[52:53], 0, v[98:99]
	v_mad_i64_i32 v[100:101], s[14:15], s8, v102, v[100:101]
	s_waitcnt lgkmcnt(0)
	s_movk_i32 s40, 0x2000
	v_add_co_u32_e32 v112, vcc, s40, v100
	s_movk_i32 s41, 0x4000
	s_nop 0
	v_addc_co_u32_e32 v113, vcc, 0, v101, vcc
	v_add_co_u32_e32 v120, vcc, s41, v100
	s_mov_b32 s43, 0xc0000
	s_nop 0
	v_addc_co_u32_e32 v121, vcc, 0, v101, vcc
	s_mov_b64 s[20:21], s[44:45]
	v_add_co_u32_e32 v128, vcc, s43, v100
	s_mov_b64 s[22:23], s[46:47]
	s_mov_b64 s[24:25], s[48:49]
	s_mov_b64 s[26:27], s[50:51]
	v_addc_co_u32_e32 v129, vcc, 0, v101, vcc
	s_mov_b32 s44, 0xc2000
	v_add_co_u32_e32 v132, vcc, s44, v100
	s_mov_b32 s45, 0xc4000
	s_nop 0
	v_addc_co_u32_e32 v133, vcc, 0, v101, vcc
	v_add_co_u32_e32 v136, vcc, s45, v100
	s_mov_b32 s46, 0x180000
	s_nop 0
	v_addc_co_u32_e32 v137, vcc, 0, v101, vcc
	v_add_co_u32_e32 v140, vcc, s46, v100
	s_mov_b32 s47, 0x182000
	s_nop 0
	v_addc_co_u32_e32 v141, vcc, 0, v101, vcc
	v_add_co_u32_e32 v144, vcc, s47, v100
	s_mov_b32 s42, 0x184000
	s_nop 0
	v_addc_co_u32_e32 v145, vcc, 0, v101, vcc
	v_add_co_u32_e32 v148, vcc, s42, v100
	s_mov_b32 s48, 0x240000
	s_nop 0
	v_addc_co_u32_e32 v149, vcc, 0, v101, vcc
	v_add_co_u32_e32 v152, vcc, s48, v100
	s_mov_b32 s49, 0x242000
	s_nop 0
	v_addc_co_u32_e32 v153, vcc, 0, v101, vcc
	s_ashr_i32 s9, s8, 31
	v_add_co_u32_e32 v156, vcc, s49, v100
	s_lshl_b64 s[12:13], s[8:9], 14
	s_nop 0
	v_addc_co_u32_e32 v157, vcc, 0, v101, vcc
	s_mov_b32 s50, 0x244000
	s_add_u32 s4, s20, s12
	s_mov_b64 s[10:11], 0x2000
	s_mov_b64 s[14:15], 0x4000
	v_add_co_u32_e32 v160, vcc, s50, v100
	s_addc_u32 s5, s21, s13
	v_lshl_add_u64 v[116:117], v[100:101], 0, s[10:11]
	v_lshl_add_u64 v[124:125], v[100:101], 0, s[14:15]
	s_mov_b64 s[16:17], 0xc0000
	v_addc_co_u32_e32 v161, vcc, 0, v101, vcc
	s_add_u32 s6, s4, 0x2000
	global_load_dwordx4 v[104:107], v[100:101], off offset:16
	global_load_dwordx4 v[108:111], v[100:101], off
	s_nop 0
	global_load_dwordx4 v[112:115], v[112:113], off
	s_nop 0
	global_load_dwordx4 v[116:119], v[116:117], off offset:16
	s_nop 0
	global_load_dwordx4 v[120:123], v[120:121], off
	s_nop 0
	global_load_dwordx4 v[124:127], v[124:125], off offset:16
	s_mov_b64 s[20:21], 0xc2000
	global_load_dwordx4 v[128:131], v[128:129], off
	s_addc_u32 s7, s5, 0
	global_load_dwordx4 v[136:139], v[136:137], off
	s_mov_b64 s[22:23], 0xc4000
	global_load_dwordx4 v[140:143], v[140:141], off
	s_mov_b64 s[28:29], 0x180000
	global_load_dwordx4 v[152:155], v[152:153], off
	s_mov_b64 s[24:25], 0x182000
	global_load_dwordx4 v[172:175], v[160:161], off
	v_lshl_add_u64 v[160:161], v[100:101], 0, s[16:17]
	global_load_dwordx4 v[132:135], v[132:133], off
	s_mov_b64 s[36:37], 0x240000
	global_load_dwordx4 v[144:147], v[144:145], off
	s_mov_b64 s[34:35], 0x242000
	global_load_dwordx4 v[156:159], v[156:157], off
	s_mov_b64 s[26:27], 0x184000
	global_load_dwordx4 v[176:179], v[160:161], off offset:16
	v_lshl_add_u64 v[160:161], v[100:101], 0, s[20:21]
	global_load_dwordx4 v[148:151], v[148:149], off
	s_nop 0
	global_load_dwordx4 v[180:183], v98, s[6:7]
	global_load_dwordx4 v[184:187], v[160:161], off offset:16
	v_lshl_add_u64 v[160:161], v[100:101], 0, s[22:23]
	global_load_dwordx4 v[188:191], v[160:161], off offset:16
	global_load_dwordx4 v[192:195], v98, s[4:5]
	v_lshl_add_u64 v[160:161], v[100:101], 0, s[28:29]
	global_load_dwordx4 v[196:199], v[160:161], off offset:16
	v_lshl_add_u64 v[160:161], v[100:101], 0, s[24:25]
	global_load_dwordx4 v[200:203], v[160:161], off offset:16
	v_lshl_add_u64 v[160:161], v[100:101], 0, s[36:37]
	global_load_dwordx4 v[204:207], v[160:161], off offset:16
	v_lshl_add_u64 v[160:161], v[100:101], 0, s[34:35]
	global_load_dwordx4 v[208:211], v[160:161], off offset:16
	s_mov_b64 s[30:31], 0x244000
	v_lshl_add_u64 v[160:161], v[100:101], 0, s[26:27]
	v_lshl_add_u64 v[100:101], v[100:101], 0, s[30:31]
	global_load_dwordx4 v[212:215], v[160:161], off offset:16
	global_load_dwordx4 v[216:219], v[100:101], off offset:16
	global_load_dwordx4 v[220:223], v98, s[6:7] offset:16
	global_load_dwordx4 v[224:227], v98, s[4:5] offset:16
	s_lshl_b64 s[38:39], s[8:9], 12
	s_add_u32 s38, s18, s38
	s_addc_u32 s39, s19, s39
	s_add_u32 s12, s92, s12
	s_addc_u32 s13, s93, s13
	s_add_u32 s12, s12, 0x48c8000
	s_addc_u32 s13, s13, 0
	v_lshl_add_u64 v[100:101], s[12:13], 0, v[98:99]
	v_add_co_u32_e32 v100, vcc, s40, v100
	s_mul_i32 s51, s8, 0x6000
	s_nop 0
	v_addc_co_u32_e32 v101, vcc, 0, v101, vcc
	s_mul_hi_i32 s9, s8, 0x6000
	v_mov_b32_e32 v171, v99
	v_mov_b32_e32 v165, v99
	v_mov_b32_e32 v163, v99
	s_waitcnt vmcnt(21)
	v_pk_add_f32 v[110:111], v[110:111], v[130:131]
	v_pk_add_f32 v[108:109], v[108:109], v[128:129]
	s_waitcnt vmcnt(20)
	v_pk_add_f32 v[122:123], v[122:123], v[138:139]
	v_pk_add_f32 v[120:121], v[120:121], v[136:137]
	s_waitcnt vmcnt(18)
	v_pk_add_f32 v[128:129], v[142:143], v[154:155]
	v_pk_add_f32 v[130:131], v[140:141], v[152:153]
	v_pk_add_f32 v[110:111], v[110:111], v[128:129]
	v_pk_add_f32 v[108:109], v[108:109], v[130:131]
	s_waitcnt vmcnt(16)
	v_pk_add_f32 v[114:115], v[114:115], v[134:135]
	v_pk_add_f32 v[112:113], v[112:113], v[132:133]
	s_waitcnt vmcnt(14)
	v_pk_add_f32 v[128:129], v[146:147], v[158:159]
	v_pk_add_f32 v[130:131], v[144:145], v[156:157]
	v_pk_add_f32 v[114:115], v[114:115], v[128:129]
	v_pk_add_f32 v[112:113], v[112:113], v[130:131]
	s_waitcnt vmcnt(11)
	v_pk_mul_f32 v[92:93], v[92:93], v[182:183]
	v_pk_mul_f32 v[90:91], v[90:91], v[180:181]
	v_pk_add_f32 v[128:129], v[150:151], v[174:175]
	v_pk_add_f32 v[130:131], v[148:149], v[172:173]
	v_pk_mul_f32 v[110:111], v[110:111], v[114:115]
	v_pk_mul_f32 v[108:109], v[108:109], v[112:113]
	s_waitcnt vmcnt(8)
	v_pk_fma_f32 v[88:89], v[88:89], v[194:195], v[92:93]
	v_pk_fma_f32 v[86:87], v[86:87], v[192:193], v[90:91]
	v_pk_add_f32 v[122:123], v[122:123], v[128:129]
	v_pk_add_f32 v[120:121], v[120:121], v[130:131]
	v_pk_fma_f32 v[88:89], v[96:97], v[110:111], v[88:89]
	v_pk_fma_f32 v[86:87], v[94:95], v[108:109], v[86:87]
	v_pk_mul_f32 v[88:89], v[122:123], v[88:89]
	v_pk_mul_f32 v[86:87], v[120:121], v[86:87]
	global_store_dwordx4 v98, v[180:183], s[12:13] sc1
	global_store_dwordx4 v[100:101], v[108:111], off sc1
	v_cvt_pk_bf16_f32 v86, v86, v87
	v_cvt_pk_bf16_f32 v87, v88, v89
	v_pk_add_f32 v[88:89], v[106:107], v[178:179]
	v_pk_add_f32 v[90:91], v[104:105], v[176:177]
	s_waitcnt vmcnt(7)
	v_pk_add_f32 v[92:93], v[198:199], v[206:207]
	v_pk_add_f32 v[94:95], v[196:197], v[204:205]
	v_pk_add_f32 v[88:89], v[88:89], v[92:93]
	v_pk_add_f32 v[92:93], v[90:91], v[94:95]
	v_pk_add_f32 v[90:91], v[118:119], v[186:187]
	v_pk_add_f32 v[94:95], v[116:117], v[184:185]
	s_waitcnt vmcnt(6)
	v_pk_add_f32 v[96:97], v[202:203], v[210:211]
	v_pk_add_f32 v[104:105], v[200:201], v[208:209]
	v_pk_add_f32 v[90:91], v[90:91], v[96:97]
	v_pk_add_f32 v[94:95], v[94:95], v[104:105]
	s_waitcnt vmcnt(3)
	v_pk_mul_f32 v[78:79], v[78:79], v[220:221]
	v_pk_add_f32 v[104:105], v[124:125], v[188:189]
	v_pk_add_f32 v[108:109], v[212:213], v[216:217]
	v_pk_mul_f32 v[90:91], v[88:89], v[90:91]
	v_pk_mul_f32 v[88:89], v[92:93], v[94:95]
	s_waitcnt vmcnt(2)
	v_pk_fma_f32 v[74:75], v[74:75], v[224:225], v[78:79]
	v_pk_add_f32 v[104:105], v[104:105], v[108:109]
	v_pk_mul_f32 v[80:81], v[80:81], v[222:223]
	v_pk_fma_f32 v[74:75], v[82:83], v[88:89], v[74:75]
	v_pk_add_f32 v[96:97], v[126:127], v[190:191]
	v_pk_add_f32 v[106:107], v[214:215], v[218:219]
	v_pk_fma_f32 v[76:77], v[76:77], v[226:227], v[80:81]
	v_pk_mul_f32 v[74:75], v[104:105], v[74:75]
	v_pk_add_f32 v[96:97], v[96:97], v[106:107]
	global_store_dwordx4 v98, v[220:223], s[12:13] offset:16 sc1
	global_store_dwordx4 v[100:101], v[88:91], off offset:16 sc1
	v_pk_fma_f32 v[76:77], v[84:85], v[90:91], v[76:77]
	s_nop 0
	v_cvt_pk_bf16_f32 v88, v74, v75
	v_lshlrev_b32_e32 v74, 1, v1
	v_mov_b32_e32 v75, v99
	v_pk_mul_f32 v[76:77], v[96:97], v[76:77]
	v_lshl_add_u64 v[74:75], s[38:39], 0, v[74:75]
	s_brev_b32 s38, 64
	v_cvt_pk_bf16_f32 v89, v76, v77
	v_add_co_u32_e32 v76, vcc, s38, v74
	s_add_u32 s38, s52, s51
	s_addc_u32 s39, s53, s9
	v_addc_co_u32_e32 v77, vcc, 0, v75, vcc
	v_lshl_add_u64 v[96:97], s[38:39], 0, v[170:171]
	v_add_co_u32_e32 v80, vcc, s40, v96
	global_store_dwordx4 v[76:77], v[86:89], off sc1
	s_nop 0
	v_addc_co_u32_e32 v81, vcc, 0, v97, vcc
	v_add_co_u32_e32 v84, vcc, s41, v96
	global_load_dwordx4 v[76:79], v170, s[38:39]
	s_nop 0
	v_addc_co_u32_e32 v85, vcc, 0, v97, vcc
	v_add_co_u32_e32 v88, vcc, s43, v96
	global_load_dwordx4 v[84:87], v[84:85], off
	s_nop 0
	v_addc_co_u32_e32 v89, vcc, 0, v97, vcc
	v_add_co_u32_e32 v92, vcc, s44, v96
	global_load_dwordx4 v[88:91], v[88:89], off
	s_nop 0
	v_addc_co_u32_e32 v93, vcc, 0, v97, vcc
	v_add_co_u32_e32 v104, vcc, s45, v96
	global_load_dwordx4 v[80:83], v[80:81], off
	s_nop 0
	v_addc_co_u32_e32 v105, vcc, 0, v97, vcc
	v_add_co_u32_e32 v108, vcc, s46, v96
	global_load_dwordx4 v[92:95], v[92:93], off
	s_nop 0
	v_addc_co_u32_e32 v109, vcc, 0, v97, vcc
	v_add_co_u32_e32 v112, vcc, s47, v96
	global_load_dwordx4 v[108:111], v[108:109], off
	s_nop 0
	v_addc_co_u32_e32 v113, vcc, 0, v97, vcc
	v_add_co_u32_e32 v116, vcc, s48, v96
	global_load_dwordx4 v[112:115], v[112:113], off
	s_nop 0
	v_addc_co_u32_e32 v117, vcc, 0, v97, vcc
	v_add_co_u32_e32 v124, vcc, s42, v96
	global_load_dwordx4 v[116:119], v[116:117], off
	s_nop 0
	v_addc_co_u32_e32 v125, vcc, 0, v97, vcc
	v_add_co_u32_e32 v120, vcc, s49, v96
	global_load_dwordx4 v[104:107], v[104:105], off
	s_nop 0
	v_addc_co_u32_e32 v121, vcc, 0, v97, vcc
	v_add_co_u32_e32 v128, vcc, s50, v96
	global_load_dwordx4 v[120:123], v[120:121], off
	s_nop 0
	global_load_dwordx4 v[124:127], v[124:125], off
	v_addc_co_u32_e32 v129, vcc, 0, v97, vcc
	v_lshl_add_u64 v[160:161], v[96:97], 0, s[36:37]
	global_load_dwordx4 v[128:131], v[128:129], off
	s_nop 0
	global_load_dwordx4 v[132:135], v170, s[6:7]
	global_load_dwordx4 v[136:139], v170, s[38:39] offset:16
	global_load_dwordx4 v[140:143], v98, s[4:5] offset:2048
	global_load_dwordx4 v[172:175], v[160:161], off offset:16
	v_lshl_add_u64 v[160:161], v[96:97], 0, s[20:21]
	global_load_dwordx4 v[176:179], v[160:161], off offset:16
	v_lshl_add_u64 v[160:161], v[96:97], 0, s[24:25]
	v_lshl_add_u64 v[152:153], v[96:97], 0, s[16:17]
	v_lshl_add_u64 v[156:157], v[96:97], 0, s[28:29]
	global_load_dwordx4 v[180:183], v[160:161], off offset:16
	v_lshl_add_u64 v[160:161], v[96:97], 0, s[34:35]
	v_lshl_add_u64 v[144:145], v[96:97], 0, s[10:11]
	global_load_dwordx4 v[152:155], v[152:153], off offset:16
	v_lshl_add_u64 v[148:149], v[96:97], 0, s[14:15]
	global_load_dwordx4 v[156:159], v[156:157], off offset:16
	s_mov_b64 s[38:39], 0x2000000
	global_load_dwordx4 v[184:187], v[160:161], off offset:16
	v_lshl_add_u64 v[160:161], v[96:97], 0, s[22:23]
	global_load_dwordx4 v[144:147], v[144:145], off offset:16
	v_lshl_add_u64 v[74:75], v[74:75], 0, s[38:39]
	global_load_dwordx4 v[188:191], v[160:161], off offset:16
	v_lshl_add_u64 v[160:161], v[96:97], 0, s[26:27]
	v_lshl_add_u64 v[96:97], v[96:97], 0, s[30:31]
	global_load_dwordx4 v[148:151], v[148:149], off offset:16
	s_waitcnt vmcnt(21)
	v_pk_add_f32 v[78:79], v[78:79], v[90:91]
	global_load_dwordx4 v[192:195], v[160:161], off offset:16
	global_load_dwordx4 v[196:199], v[96:97], off offset:16
	global_load_dwordx4 v[200:203], v170, s[6:7] offset:16
	global_load_dwordx4 v[204:207], v98, s[4:5] offset:2064
	v_pk_add_f32 v[76:77], v[76:77], v[88:89]
	v_lshl_add_u64 v[96:97], s[52:53], 0, v[164:165]
	v_mad_i64_i32 v[96:97], s[38:39], s8, v102, v[96:97]
	s_waitcnt vmcnt(23)
	v_pk_add_f32 v[82:83], v[82:83], v[94:95]
	v_pk_add_f32 v[80:81], v[80:81], v[92:93]
	s_waitcnt vmcnt(20)
	v_pk_add_f32 v[88:89], v[110:111], v[118:119]
	v_pk_add_f32 v[90:91], v[108:109], v[116:117]
	v_pk_add_f32 v[78:79], v[78:79], v[88:89]
	v_pk_add_f32 v[76:77], v[76:77], v[90:91]
	s_waitcnt vmcnt(19)
	v_pk_add_f32 v[86:87], v[86:87], v[106:107]
	v_pk_add_f32 v[84:85], v[84:85], v[104:105]
	s_waitcnt vmcnt(18)
	v_pk_add_f32 v[88:89], v[114:115], v[122:123]
	v_pk_add_f32 v[90:91], v[112:113], v[120:121]
	v_pk_add_f32 v[82:83], v[82:83], v[88:89]
	v_pk_add_f32 v[80:81], v[80:81], v[90:91]
	s_waitcnt vmcnt(15)
	v_pk_mul_f32 v[68:69], v[68:69], v[134:135]
	v_pk_mul_f32 v[66:67], v[66:67], v[132:133]
	v_pk_add_f32 v[88:89], v[126:127], v[130:131]
	v_pk_add_f32 v[90:91], v[124:125], v[128:129]
	v_pk_mul_f32 v[78:79], v[78:79], v[82:83]
	v_pk_mul_f32 v[76:77], v[76:77], v[80:81]
	s_waitcnt vmcnt(13)
	v_pk_fma_f32 v[64:65], v[64:65], v[142:143], v[68:69]
	v_pk_fma_f32 v[62:63], v[62:63], v[140:141], v[66:67]
	v_pk_add_f32 v[86:87], v[86:87], v[88:89]
	v_pk_add_f32 v[84:85], v[84:85], v[90:91]
	v_pk_fma_f32 v[64:65], v[72:73], v[78:79], v[64:65]
	v_pk_fma_f32 v[62:63], v[70:71], v[76:77], v[62:63]
	v_pk_mul_f32 v[64:65], v[86:87], v[64:65]
	v_pk_mul_f32 v[62:63], v[84:85], v[62:63]
	global_store_dwordx4 v98, v[132:135], s[12:13] offset:2048 sc1
	global_store_dwordx4 v[100:101], v[76:79], off offset:2048 sc1
	v_cvt_pk_bf16_f32 v62, v62, v63
	v_cvt_pk_bf16_f32 v63, v64, v65
	s_waitcnt vmcnt(11)
	v_pk_add_f32 v[64:65], v[138:139], v[154:155]
	v_pk_add_f32 v[66:67], v[136:137], v[152:153]
	s_waitcnt vmcnt(10)
	v_pk_add_f32 v[68:69], v[158:159], v[174:175]
	v_pk_add_f32 v[70:71], v[156:157], v[172:173]
	v_pk_add_f32 v[64:65], v[64:65], v[68:69]
	v_pk_add_f32 v[68:69], v[66:67], v[70:71]
	s_waitcnt vmcnt(8)
	v_pk_add_f32 v[66:67], v[146:147], v[178:179]
	v_pk_add_f32 v[70:71], v[144:145], v[176:177]
	v_pk_add_f32 v[72:73], v[182:183], v[186:187]
	v_pk_add_f32 v[76:77], v[180:181], v[184:185]
	v_pk_add_f32 v[66:67], v[66:67], v[72:73]
	v_pk_add_f32 v[70:71], v[70:71], v[76:77]
	v_pk_mul_f32 v[66:67], v[64:65], v[66:67]
	v_pk_mul_f32 v[64:65], v[68:69], v[70:71]
	s_waitcnt vmcnt(6)
	v_pk_add_f32 v[72:73], v[150:151], v[190:191]
	v_pk_add_f32 v[76:77], v[148:149], v[188:189]
	s_waitcnt vmcnt(3)
	global_store_dwordx4 v98, v[200:203], s[12:13] offset:2064 sc1
	global_store_dwordx4 v[100:101], v[64:67], off offset:2064 sc1
	v_pk_mul_f32 v[54:55], v[54:55], v[200:201]
	v_pk_mul_f32 v[56:57], v[56:57], v[202:203]
	s_waitcnt vmcnt(4)
	v_pk_fma_f32 v[50:51], v[50:51], v[204:205], v[54:55]
	v_add_co_u32_e32 v54, vcc, s40, v96
	v_pk_add_f32 v[78:79], v[194:195], v[198:199]
	s_nop 0
	v_addc_co_u32_e32 v55, vcc, 0, v97, vcc
	v_pk_add_f32 v[80:81], v[192:193], v[196:197]
	v_pk_fma_f32 v[52:53], v[52:53], v[206:207], v[56:57]
	v_pk_fma_f32 v[50:51], v[58:59], v[64:65], v[50:51]
	v_add_co_u32_e32 v58, vcc, s41, v96
	v_pk_add_f32 v[72:73], v[72:73], v[78:79]
	v_pk_add_f32 v[76:77], v[76:77], v[80:81]
	v_pk_fma_f32 v[52:53], v[60:61], v[66:67], v[52:53]
	v_addc_co_u32_e32 v59, vcc, 0, v97, vcc
	v_pk_mul_f32 v[52:53], v[72:73], v[52:53]
	v_pk_mul_f32 v[50:51], v[76:77], v[50:51]
	v_lshl_add_u64 v[98:99], s[12:13], 0, v[164:165]
	v_cvt_pk_bf16_f32 v64, v50, v51
	v_cvt_pk_bf16_f32 v65, v52, v53
	global_store_dwordx4 v[74:75], v[62:65], off offset:1024 sc1
	global_load_dwordx4 v[50:53], v[96:97], off
	s_nop 0
	v_add_co_u32_e32 v62, vcc, s43, v96
	global_load_dwordx4 v[54:57], v[54:55], off
	s_nop 0
	v_addc_co_u32_e32 v63, vcc, 0, v97, vcc
	v_add_co_u32_e32 v66, vcc, s44, v96
	global_load_dwordx4 v[58:61], v[58:59], off
	s_nop 0
	v_addc_co_u32_e32 v67, vcc, 0, v97, vcc
	v_add_co_u32_e32 v70, vcc, s45, v96
	global_load_dwordx4 v[62:65], v[62:63], off
	s_nop 0
	v_addc_co_u32_e32 v71, vcc, 0, v97, vcc
	v_add_co_u32_e32 v76, vcc, s46, v96
	global_load_dwordx4 v[66:69], v[66:67], off
	s_nop 0
	v_addc_co_u32_e32 v77, vcc, 0, v97, vcc
	v_add_co_u32_e32 v80, vcc, s47, v96
	global_load_dwordx4 v[70:73], v[70:71], off
	s_nop 0
	v_addc_co_u32_e32 v81, vcc, 0, v97, vcc
	v_add_co_u32_e32 v84, vcc, s48, v96
	global_load_dwordx4 v[76:79], v[76:77], off
	s_nop 0
	v_addc_co_u32_e32 v85, vcc, 0, v97, vcc
	v_add_co_u32_e32 v92, vcc, s42, v96
	global_load_dwordx4 v[80:83], v[80:81], off
	s_nop 0
	v_addc_co_u32_e32 v93, vcc, 0, v97, vcc
	v_add_co_u32_e32 v88, vcc, s49, v96
	global_load_dwordx4 v[84:87], v[84:85], off
	s_nop 0
	v_addc_co_u32_e32 v89, vcc, 0, v97, vcc
	v_add_co_u32_e32 v100, vcc, s50, v96
	global_load_dwordx4 v[88:91], v[88:89], off
	s_nop 0
	global_load_dwordx4 v[92:95], v[92:93], off
	v_addc_co_u32_e32 v101, vcc, 0, v97, vcc
	global_load_dwordx4 v[104:107], v[100:101], off
	global_load_dwordx4 v[108:111], v164, s[6:7]
	global_load_dwordx4 v[112:115], v[96:97], off offset:16
	global_load_dwordx4 v[116:119], v164, s[4:5]
	v_lshl_add_u64 v[100:101], v[96:97], 0, s[10:11]
	global_load_dwordx4 v[120:123], v[100:101], off offset:16
	v_lshl_add_u64 v[100:101], v[96:97], 0, s[14:15]
	global_load_dwordx4 v[124:127], v[100:101], off offset:16
	v_lshl_add_u64 v[100:101], v[96:97], 0, s[16:17]
	global_load_dwordx4 v[128:131], v[100:101], off offset:16
	v_lshl_add_u64 v[100:101], v[96:97], 0, s[28:29]
	global_load_dwordx4 v[132:135], v[100:101], off offset:16
	v_lshl_add_u64 v[100:101], v[96:97], 0, s[36:37]
	global_load_dwordx4 v[136:139], v[100:101], off offset:16
	v_lshl_add_u64 v[100:101], v[96:97], 0, s[20:21]
	global_load_dwordx4 v[140:143], v[100:101], off offset:16
	v_lshl_add_u64 v[100:101], v[96:97], 0, s[24:25]
	global_load_dwordx4 v[144:147], v[100:101], off offset:16
	v_lshl_add_u64 v[100:101], v[96:97], 0, s[34:35]
	global_load_dwordx4 v[148:151], v[100:101], off offset:16
	v_lshl_add_u64 v[100:101], v[96:97], 0, s[22:23]
	global_load_dwordx4 v[152:155], v[100:101], off offset:16
	v_lshl_add_u64 v[100:101], v[96:97], 0, s[26:27]
	v_lshl_add_u64 v[96:97], v[96:97], 0, s[30:31]
	global_load_dwordx4 v[156:159], v[100:101], off offset:16
	global_load_dwordx4 v[170:173], v[96:97], off offset:16
	global_load_dwordx4 v[174:177], v164, s[6:7] offset:16
	global_load_dwordx4 v[178:181], v164, s[4:5] offset:16
	v_lshl_add_u64 v[96:97], s[52:53], 0, v[162:163]
	s_waitcnt vmcnt(24)
	v_pk_add_f32 v[52:53], v[52:53], v[64:65]
	v_pk_add_f32 v[50:51], v[50:51], v[62:63]
	s_waitcnt vmcnt(23)
	v_pk_add_f32 v[56:57], v[56:57], v[68:69]
	v_pk_add_f32 v[54:55], v[54:55], v[66:67]
	s_waitcnt vmcnt(22)
	v_pk_add_f32 v[60:61], v[60:61], v[72:73]
	v_pk_add_f32 v[58:59], v[58:59], v[70:71]
	s_waitcnt vmcnt(19)
	v_pk_add_f32 v[62:63], v[78:79], v[86:87]
	v_pk_add_f32 v[64:65], v[76:77], v[84:85]
	v_pk_add_f32 v[52:53], v[52:53], v[62:63]
	v_pk_add_f32 v[50:51], v[50:51], v[64:65]
	s_waitcnt vmcnt(18)
	v_pk_add_f32 v[62:63], v[82:83], v[90:91]
	v_pk_add_f32 v[64:65], v[80:81], v[88:89]
	v_pk_add_f32 v[56:57], v[56:57], v[62:63]
	v_pk_add_f32 v[54:55], v[54:55], v[64:65]
	s_waitcnt vmcnt(15)
	v_pk_mul_f32 v[44:45], v[44:45], v[110:111]
	v_pk_mul_f32 v[42:43], v[42:43], v[108:109]
	v_pk_add_f32 v[62:63], v[94:95], v[106:107]
	v_pk_add_f32 v[64:65], v[92:93], v[104:105]
	v_pk_mul_f32 v[52:53], v[52:53], v[56:57]
	v_pk_mul_f32 v[50:51], v[50:51], v[54:55]
	s_waitcnt vmcnt(13)
	v_pk_fma_f32 v[40:41], v[40:41], v[118:119], v[44:45]
	v_pk_fma_f32 v[38:39], v[38:39], v[116:117], v[42:43]
	v_pk_add_f32 v[60:61], v[60:61], v[62:63]
	v_pk_add_f32 v[58:59], v[58:59], v[64:65]
	v_add_co_u32_e32 v54, vcc, s40, v98
	v_pk_fma_f32 v[40:41], v[48:49], v[52:53], v[40:41]
	v_pk_fma_f32 v[38:39], v[46:47], v[50:51], v[38:39]
	v_addc_co_u32_e32 v55, vcc, 0, v99, vcc
	v_pk_mul_f32 v[40:41], v[60:61], v[40:41]
	v_pk_mul_f32 v[38:39], v[58:59], v[38:39]
	global_store_dwordx4 v164, v[108:111], s[12:13] sc1
	global_store_dwordx4 v[54:55], v[50:53], off sc1
	v_cvt_pk_bf16_f32 v38, v38, v39
	v_cvt_pk_bf16_f32 v39, v40, v41
	s_waitcnt vmcnt(12)
	v_pk_add_f32 v[40:41], v[114:115], v[130:131]
	v_pk_add_f32 v[42:43], v[112:113], v[128:129]
	s_waitcnt vmcnt(10)
	v_pk_add_f32 v[44:45], v[134:135], v[138:139]
	v_pk_add_f32 v[46:47], v[132:133], v[136:137]
	v_pk_add_f32 v[40:41], v[40:41], v[44:45]
	v_pk_add_f32 v[44:45], v[42:43], v[46:47]
	s_waitcnt vmcnt(9)
	v_pk_add_f32 v[42:43], v[122:123], v[142:143]
	v_pk_add_f32 v[46:47], v[120:121], v[140:141]
	s_waitcnt vmcnt(7)
	v_pk_add_f32 v[48:49], v[146:147], v[150:151]
	v_pk_add_f32 v[50:51], v[144:145], v[148:149]
	s_waitcnt vmcnt(3)
	v_pk_mul_f32 v[30:31], v[30:31], v[174:175]
	v_mad_i64_i32 v[128:129], s[8:9], s8, v102, v[96:97]
	v_pk_add_f32 v[42:43], v[42:43], v[48:49]
	v_pk_add_f32 v[46:47], v[46:47], v[50:51]
	s_waitcnt vmcnt(2)
	v_pk_fma_f32 v[26:27], v[26:27], v[178:179], v[30:31]
	v_add_co_u32_e32 v30, vcc, s40, v128
	v_pk_mul_f32 v[42:43], v[40:41], v[42:43]
	v_pk_mul_f32 v[40:41], v[44:45], v[46:47]
	v_pk_mul_f32 v[32:33], v[32:33], v[176:177]
	v_addc_co_u32_e32 v31, vcc, 0, v129, vcc
	v_pk_add_f32 v[48:49], v[126:127], v[154:155]
	v_pk_add_f32 v[50:51], v[124:125], v[152:153]
	v_pk_add_f32 v[52:53], v[158:159], v[172:173]
	v_pk_add_f32 v[56:57], v[156:157], v[170:171]
	v_pk_fma_f32 v[28:29], v[28:29], v[180:181], v[32:33]
	v_pk_fma_f32 v[26:27], v[34:35], v[40:41], v[26:27]
	v_add_co_u32_e32 v34, vcc, s41, v128
	v_pk_add_f32 v[48:49], v[48:49], v[52:53]
	v_pk_add_f32 v[50:51], v[50:51], v[56:57]
	v_pk_fma_f32 v[28:29], v[36:37], v[42:43], v[28:29]
	v_addc_co_u32_e32 v35, vcc, 0, v129, vcc
	global_store_dwordx4 v164, v[174:177], s[12:13] offset:16 sc1
	global_store_dwordx4 v[54:55], v[40:43], off offset:16 sc1
	v_pk_mul_f32 v[28:29], v[48:49], v[28:29]
	v_pk_mul_f32 v[26:27], v[50:51], v[26:27]
	v_lshl_add_u64 v[96:97], v[128:129], 0, s[16:17]
	v_cvt_pk_bf16_f32 v40, v26, v27
	v_cvt_pk_bf16_f32 v41, v28, v29
	global_store_dwordx4 v[74:75], v[38:41], off offset:2048 sc1
	global_load_dwordx4 v[26:29], v[128:129], off
	v_lshl_add_u64 v[100:101], v[128:129], 0, s[28:29]
	v_add_co_u32_e32 v38, vcc, s43, v128
	global_load_dwordx4 v[30:33], v[30:31], off
	s_nop 0
	v_addc_co_u32_e32 v39, vcc, 0, v129, vcc
	v_add_co_u32_e32 v42, vcc, s44, v128
	global_load_dwordx4 v[38:41], v[38:39], off
	s_nop 0
	v_addc_co_u32_e32 v43, vcc, 0, v129, vcc
	v_add_co_u32_e32 v46, vcc, s45, v128
	global_load_dwordx4 v[42:45], v[42:43], off
	s_nop 0
	v_addc_co_u32_e32 v47, vcc, 0, v129, vcc
	v_add_co_u32_e32 v50, vcc, s46, v128
	global_load_dwordx4 v[46:49], v[46:47], off
	s_nop 0
	v_addc_co_u32_e32 v51, vcc, 0, v129, vcc
	v_add_co_u32_e32 v54, vcc, s47, v128
	global_load_dwordx4 v[50:53], v[50:51], off
	s_nop 0
	v_addc_co_u32_e32 v55, vcc, 0, v129, vcc
	v_add_co_u32_e32 v58, vcc, s48, v128
	global_load_dwordx4 v[54:57], v[54:55], off
	s_nop 0
	v_addc_co_u32_e32 v59, vcc, 0, v129, vcc
	v_add_co_u32_e32 v66, vcc, s42, v128
	global_load_dwordx4 v[58:61], v[58:59], off
	s_nop 0
	v_addc_co_u32_e32 v67, vcc, 0, v129, vcc
	v_add_co_u32_e32 v62, vcc, s49, v128
	global_load_dwordx4 v[34:37], v[34:35], off
	s_nop 0
	v_addc_co_u32_e32 v63, vcc, 0, v129, vcc
	v_add_co_u32_e32 v70, vcc, s50, v128
	global_load_dwordx4 v[62:65], v[62:63], off
	s_nop 0
	global_load_dwordx4 v[66:69], v[66:67], off
	v_addc_co_u32_e32 v71, vcc, 0, v129, vcc
	global_load_dwordx4 v[70:73], v[70:71], off
	s_nop 0
	global_load_dwordx4 v[76:79], v162, s[6:7]
	global_load_dwordx4 v[80:83], v[128:129], off offset:16
	global_load_dwordx4 v[84:87], v162, s[4:5]
	v_lshl_add_u64 v[104:105], v[128:129], 0, s[36:37]
	v_lshl_add_u64 v[88:89], v[128:129], 0, s[10:11]
	global_load_dwordx4 v[96:99], v[96:97], off offset:16
	v_lshl_add_u64 v[108:109], v[128:129], 0, s[20:21]
	global_load_dwordx4 v[100:103], v[100:101], off offset:16
	v_lshl_add_u64 v[112:113], v[128:129], 0, s[24:25]
	global_load_dwordx4 v[104:107], v[104:105], off offset:16
	v_lshl_add_u64 v[116:117], v[128:129], 0, s[34:35]
	global_load_dwordx4 v[88:91], v[88:89], off offset:16
	v_lshl_add_u64 v[92:93], v[128:129], 0, s[14:15]
	global_load_dwordx4 v[108:111], v[108:109], off offset:16
	v_lshl_add_u64 v[120:121], v[128:129], 0, s[22:23]
	global_load_dwordx4 v[112:115], v[112:113], off offset:16
	v_lshl_add_u64 v[124:125], v[128:129], 0, s[26:27]
	global_load_dwordx4 v[116:119], v[116:117], off offset:16
	v_lshl_add_u64 v[128:129], v[128:129], 0, s[30:31]
	global_load_dwordx4 v[92:95], v[92:93], off offset:16
	v_lshl_add_u64 v[140:141], s[12:13], 0, v[162:163]
	global_load_dwordx4 v[120:123], v[120:121], off offset:16
	s_waitcnt vmcnt(21)
	v_pk_add_f32 v[28:29], v[28:29], v[40:41]
	global_load_dwordx4 v[124:127], v[124:125], off offset:16
	s_nop 0
	global_load_dwordx4 v[128:131], v[128:129], off offset:16
	s_nop 0
	global_load_dwordx4 v[132:135], v162, s[6:7] offset:16
	global_load_dwordx4 v[136:139], v162, s[4:5] offset:16
	v_pk_add_f32 v[26:27], v[26:27], v[38:39]
	s_waitcnt vmcnt(24)
	v_pk_add_f32 v[32:33], v[32:33], v[44:45]
	v_pk_add_f32 v[30:31], v[30:31], v[42:43]
	s_waitcnt vmcnt(20)
	v_pk_add_f32 v[38:39], v[52:53], v[60:61]
	v_pk_add_f32 v[40:41], v[50:51], v[58:59]
	v_pk_add_f32 v[28:29], v[28:29], v[38:39]
	v_pk_add_f32 v[26:27], v[26:27], v[40:41]
	s_waitcnt vmcnt(19)
	v_pk_add_f32 v[36:37], v[36:37], v[48:49]
	v_pk_add_f32 v[34:35], v[34:35], v[46:47]
	s_waitcnt vmcnt(18)
	v_pk_add_f32 v[38:39], v[56:57], v[64:65]
	v_pk_add_f32 v[40:41], v[54:55], v[62:63]
	v_pk_add_f32 v[32:33], v[32:33], v[38:39]
	v_pk_add_f32 v[30:31], v[30:31], v[40:41]
	s_waitcnt vmcnt(15)
	v_pk_mul_f32 v[20:21], v[20:21], v[78:79]
	v_pk_mul_f32 v[18:19], v[18:19], v[76:77]
	v_pk_add_f32 v[38:39], v[68:69], v[72:73]
	v_pk_add_f32 v[40:41], v[66:67], v[70:71]
	v_pk_mul_f32 v[28:29], v[28:29], v[32:33]
	v_pk_mul_f32 v[26:27], v[26:27], v[30:31]
	s_waitcnt vmcnt(13)
	v_pk_fma_f32 v[16:17], v[16:17], v[86:87], v[20:21]
	v_pk_fma_f32 v[14:15], v[14:15], v[84:85], v[18:19]
	v_pk_add_f32 v[36:37], v[36:37], v[38:39]
	v_pk_add_f32 v[34:35], v[34:35], v[40:41]
	v_add_co_u32_e32 v30, vcc, s40, v140
	v_pk_fma_f32 v[16:17], v[24:25], v[28:29], v[16:17]
	v_pk_fma_f32 v[14:15], v[22:23], v[26:27], v[14:15]
	v_addc_co_u32_e32 v31, vcc, 0, v141, vcc
	v_pk_mul_f32 v[16:17], v[36:37], v[16:17]
	v_pk_mul_f32 v[14:15], v[34:35], v[14:15]
	global_store_dwordx4 v162, v[76:79], s[12:13] sc1
	global_store_dwordx4 v[30:31], v[26:29], off sc1
	v_cvt_pk_bf16_f32 v14, v14, v15
	v_cvt_pk_bf16_f32 v15, v16, v17
	s_waitcnt vmcnt(14)
	v_pk_add_f32 v[16:17], v[82:83], v[98:99]
	v_pk_add_f32 v[18:19], v[80:81], v[96:97]
	s_waitcnt vmcnt(12)
	v_pk_add_f32 v[20:21], v[102:103], v[106:107]
	v_pk_add_f32 v[22:23], v[100:101], v[104:105]
	v_pk_add_f32 v[16:17], v[16:17], v[20:21]
	v_pk_add_f32 v[20:21], v[18:19], v[22:23]
	s_waitcnt vmcnt(10)
	v_pk_add_f32 v[18:19], v[90:91], v[110:111]
	v_pk_add_f32 v[22:23], v[88:89], v[108:109]
	s_waitcnt vmcnt(8)
	v_pk_add_f32 v[24:25], v[114:115], v[118:119]
	v_pk_add_f32 v[26:27], v[112:113], v[116:117]
	v_pk_add_f32 v[18:19], v[18:19], v[24:25]
	v_pk_add_f32 v[22:23], v[22:23], v[26:27]
	s_waitcnt vmcnt(6)
	v_pk_add_f32 v[24:25], v[94:95], v[122:123]
	v_pk_add_f32 v[26:27], v[92:93], v[120:121]
	v_pk_mul_f32 v[18:19], v[16:17], v[18:19]
	v_pk_mul_f32 v[16:17], v[20:21], v[22:23]
	s_waitcnt vmcnt(3)
	global_store_dwordx4 v162, v[132:135], s[12:13] offset:16 sc1
	global_store_dwordx4 v[30:31], v[16:19], off offset:16 sc1
	v_pk_mul_f32 v[8:9], v[8:9], v[134:135]
	v_pk_mul_f32 v[6:7], v[6:7], v[132:133]
	v_pk_add_f32 v[28:29], v[126:127], v[130:131]
	v_pk_add_f32 v[32:33], v[124:125], v[128:129]
	s_waitcnt vmcnt(4)
	v_pk_fma_f32 v[4:5], v[4:5], v[138:139], v[8:9]
	v_pk_fma_f32 v[2:3], v[2:3], v[136:137], v[6:7]
	v_pk_add_f32 v[24:25], v[24:25], v[28:29]
	v_pk_add_f32 v[26:27], v[26:27], v[32:33]
	v_pk_fma_f32 v[4:5], v[12:13], v[18:19], v[4:5]
	v_pk_fma_f32 v[2:3], v[10:11], v[16:17], v[2:3]
	v_pk_mul_f32 v[4:5], v[24:25], v[4:5]
	v_pk_mul_f32 v[2:3], v[26:27], v[2:3]
	s_nop 0
	v_cvt_pk_bf16_f32 v16, v2, v3
	v_cvt_pk_bf16_f32 v17, v4, v5
	global_store_dwordx4 v[74:75], v[14:17], off offset:3072 sc1

.LBB0_3083:
	v_lshlrev_b32_e32 v105, 16, v94
	v_and_b32_e32 v94, 0xffff0000, v94
	v_add_f32_e32 v106, v105, v94
	v_lshlrev_b32_e32 v107, 16, v95
	v_and_b32_e32 v95, 0xffff0000, v95
	v_add_f32_e32 v106, 0, v106
	v_add_f32_e32 v108, v107, v95
	v_add_f32_e32 v106, v108, v106
	v_lshlrev_b32_e32 v108, 16, v96
	v_and_b32_e32 v96, 0xffff0000, v96
	v_add_f32_e32 v109, v108, v96
	v_add_f32_e32 v106, v109, v106
	v_lshlrev_b32_e32 v109, 16, v97
	v_and_b32_e32 v97, 0xffff0000, v97
	v_add_f32_e32 v110, v109, v97
	v_add_f32_e32 v106, v110, v106
	v_lshlrev_b32_e32 v110, 16, v90
	v_and_b32_e32 v90, 0xffff0000, v90
	v_add_f32_e32 v111, v110, v90
	v_add_f32_e32 v106, v111, v106
	v_lshlrev_b32_e32 v111, 16, v91
	v_and_b32_e32 v91, 0xffff0000, v91
	v_add_f32_e32 v112, v111, v91
	v_add_f32_e32 v106, v112, v106
	v_lshlrev_b32_e32 v112, 16, v92
	v_and_b32_e32 v92, 0xffff0000, v92
	v_add_f32_e32 v113, v112, v92
	v_add_f32_e32 v106, v113, v106
	v_lshlrev_b32_e32 v113, 16, v93
	v_and_b32_e32 v93, 0xffff0000, v93
	v_add_f32_e32 v114, v113, v93
	v_add_f32_e32 v106, v114, v106
	v_lshlrev_b32_e32 v114, 16, v86
	v_and_b32_e32 v115, 0xffff0000, v86
	v_add_f32_e32 v86, v114, v115
	v_add_f32_e32 v86, v86, v106
	v_lshlrev_b32_e32 v106, 16, v87
	v_and_b32_e32 v116, 0xffff0000, v87
	v_add_f32_e32 v87, v106, v116
	v_lshlrev_b32_e32 v117, 16, v88
	v_and_b32_e32 v88, 0xffff0000, v88
	v_add_f32_e32 v86, v87, v86
	v_add_f32_e32 v87, v117, v88
	v_lshlrev_b32_e32 v118, 16, v89
	v_and_b32_e32 v89, 0xffff0000, v89
	v_add_f32_e32 v86, v87, v86
	v_add_f32_e32 v87, v118, v89
	v_lshlrev_b32_e32 v119, 16, v82
	v_and_b32_e32 v120, 0xffff0000, v82
	v_add_f32_e32 v86, v87, v86
	v_add_f32_e32 v82, v119, v120
	v_lshlrev_b32_e32 v121, 16, v83
	v_and_b32_e32 v122, 0xffff0000, v83
	v_add_f32_e32 v82, v82, v86
	v_add_f32_e32 v83, v121, v122
	v_lshlrev_b32_e32 v123, 16, v84
	v_and_b32_e32 v124, 0xffff0000, v84
	v_add_f32_e32 v82, v83, v82
	v_add_f32_e32 v83, v123, v124
	v_lshlrev_b32_e32 v125, 16, v85
	v_and_b32_e32 v126, 0xffff0000, v85
	v_add_f32_e32 v82, v83, v82
	v_add_f32_e32 v83, v125, v126
	v_add_f32_e32 v82, v83, v82
	v_mov_b32_e32 v83, 0
	s_nop 0
	v_add_f32_dpp v82, v82, v82 quad_perm:[1,0,3,2] row_mask:0xf bank_mask:0xf bound_ctrl:1
	s_nop 1
	v_add_f32_dpp v82, v82, v82 quad_perm:[2,3,0,1] row_mask:0xf bank_mask:0xf bound_ctrl:1
	s_nop 1
	v_add_f32_dpp v82, v82, v82 row_half_mirror row_mask:0xf bank_mask:0xf bound_ctrl:1
	s_nop 1
	v_add_f32_dpp v82, v82, v82 row_mirror row_mask:0xf bank_mask:0xf bound_ctrl:1
	s_nop 1
	v_mov_b32_dpp v83, v82 row_bcast:15 row_mask:0xa bank_mask:0xf
	v_add_f32_e32 v82, v82, v83
	v_mov_b32_e32 v83, 0
	s_nop 1
	v_mov_b32_dpp v83, v82 row_bcast:31 row_mask:0xc bank_mask:0xf
	v_add_f32_e32 v82, v82, v83
	v_mov_b32_e32 v83, 0
	v_readlane_b32 s7, v82, 63
	s_nop 1
	v_fmac_f32_e32 v94, s7, v103
	v_fmac_f32_e32 v105, s7, v103
	v_mul_f32_e32 v82, v94, v94
	v_fmac_f32_e32 v82, v105, v105
	v_fmac_f32_e32 v107, s7, v103
	v_fmac_f32_e32 v82, v107, v107
	v_fmac_f32_e32 v95, s7, v103
	v_fmac_f32_e32 v82, v95, v95
	v_fmac_f32_e32 v108, s7, v103
	v_fmac_f32_e32 v82, v108, v108
	v_fmac_f32_e32 v96, s7, v103
	v_fmac_f32_e32 v82, v96, v96
	v_fmac_f32_e32 v109, s7, v103
	v_fmac_f32_e32 v82, v109, v109
	v_fmac_f32_e32 v97, s7, v103
	v_fmac_f32_e32 v82, v97, v97
	v_fmac_f32_e32 v110, s7, v103
	v_fmac_f32_e32 v82, v110, v110
	v_fmac_f32_e32 v90, s7, v103
	v_fmac_f32_e32 v82, v90, v90
	v_fmac_f32_e32 v111, s7, v103
	v_fmac_f32_e32 v82, v111, v111
	v_fmac_f32_e32 v91, s7, v103
	v_fmac_f32_e32 v82, v91, v91
	v_fmac_f32_e32 v112, s7, v103
	v_fmac_f32_e32 v82, v112, v112
	v_fmac_f32_e32 v92, s7, v103
	v_fmac_f32_e32 v82, v92, v92
	v_fmac_f32_e32 v113, s7, v103
	v_fmac_f32_e32 v82, v113, v113
	v_fmac_f32_e32 v93, s7, v103
	v_fmac_f32_e32 v82, v93, v93
	v_fmac_f32_e32 v114, s7, v103
	v_fmac_f32_e32 v82, v114, v114
	v_fmac_f32_e32 v115, s7, v103
	v_fmac_f32_e32 v82, v115, v115
	v_fmac_f32_e32 v106, s7, v103
	v_fmac_f32_e32 v82, v106, v106
	v_fmac_f32_e32 v116, s7, v103
	v_fmac_f32_e32 v82, v116, v116
	v_fmac_f32_e32 v117, s7, v103
	v_fmac_f32_e32 v82, v117, v117
	v_fmac_f32_e32 v88, s7, v103
	v_fmac_f32_e32 v82, v88, v88
	v_fmac_f32_e32 v118, s7, v103
	v_fmac_f32_e32 v82, v118, v118
	v_fmac_f32_e32 v89, s7, v103
	v_fmac_f32_e32 v82, v89, v89
	v_fmac_f32_e32 v119, s7, v103
	v_fmac_f32_e32 v82, v119, v119
	v_fmac_f32_e32 v120, s7, v103
	v_fmac_f32_e32 v82, v120, v120
	v_fmac_f32_e32 v121, s7, v103
	v_fmac_f32_e32 v82, v121, v121
	v_fmac_f32_e32 v122, s7, v103
	v_fmac_f32_e32 v82, v122, v122
	v_fmac_f32_e32 v123, s7, v103
	v_fmac_f32_e32 v82, v123, v123
	v_fmac_f32_e32 v124, s7, v103
	v_fmac_f32_e32 v82, v124, v124
	v_fmac_f32_e32 v125, s7, v103
	v_fmac_f32_e32 v82, v125, v125
	v_fmac_f32_e32 v126, s7, v103
	v_fmac_f32_e32 v82, v126, v126
	s_nop 1
	v_add_f32_dpp v82, v82, v82 quad_perm:[1,0,3,2] row_mask:0xf bank_mask:0xf bound_ctrl:1
	s_nop 1
	v_add_f32_dpp v82, v82, v82 quad_perm:[2,3,0,1] row_mask:0xf bank_mask:0xf bound_ctrl:1
	s_nop 1
	v_add_f32_dpp v82, v82, v82 row_half_mirror row_mask:0xf bank_mask:0xf bound_ctrl:1
	s_nop 1
	v_add_f32_dpp v82, v82, v82 row_mirror row_mask:0xf bank_mask:0xf bound_ctrl:1
	s_nop 1
	v_mov_b32_dpp v83, v82 row_bcast:15 row_mask:0xa bank_mask:0xf
	v_add_f32_e32 v82, v82, v83
	v_mov_b32_e32 v83, 0
	s_nop 1
	v_mov_b32_dpp v83, v82 row_bcast:31 row_mask:0xc bank_mask:0xf
	v_add_f32_e32 v82, v82, v83
	s_nop 0
	v_readlane_b32 s7, v82, 63
	s_nop 1
	v_fma_f32 v82, s7, v104, v102
	v_rsq_f32_e32 v127, v82
	s_nop 0
	v_mul_f32_e32 v82, v105, v127
	v_mul_f32_e32 v83, v94, v127
	v_mul_f32_e32 v84, v107, v127
	v_mul_f32_e32 v86, v108, v127
	v_mul_f32_e32 v87, v96, v127
	v_fma_f32 v82, v58, v82, v62
	v_fma_f32 v83, v59, v83, v63
	v_fma_f32 v84, v60, v84, v64
	v_mul_f32_e32 v85, v95, v127
	v_fma_f32 v86, v50, v86, v54
	v_fma_f32 v87, v51, v87, v55
	v_fma_f32 v85, v61, v85, v65
	v_cvt_pk_bf16_f32 v82, v82, v83
	v_cvt_pk_bf16_f32 v83, v84, v85
	v_cvt_pk_bf16_f32 v84, v86, v87
	v_lshl_add_u64 v[86:87], s[8:9], 0, v[98:99]
	v_mul_f32_e32 v94, v109, v127
	v_mul_f32_e32 v95, v97, v127
	v_add_co_u32_e32 v86, vcc, s5, v86
	v_fma_f32 v94, v52, v94, v56
	v_fma_f32 v95, v53, v95, v57
	v_cvt_pk_bf16_f32 v85, v94, v95
	v_addc_co_u32_e32 v87, vcc, 0, v87, vcc
	global_store_dwordx4 v[86:87], v[82:85], off sc1
	v_mul_f32_e32 v93, v93, v127
	v_fma_f32 v93, v37, v93, v41
	v_mul_f32_e32 v82, v110, v127
	v_mul_f32_e32 v83, v90, v127
	v_mul_f32_e32 v84, v111, v127
	v_mul_f32_e32 v85, v91, v127
	v_fma_f32 v82, v42, v82, v46
	v_fma_f32 v83, v43, v83, v47
	v_fma_f32 v84, v44, v84, v48
	v_fma_f32 v85, v45, v85, v49
	v_mul_f32_e32 v90, v112, v127
	v_mul_f32_e32 v91, v92, v127
	v_mul_f32_e32 v92, v113, v127
	v_fma_f32 v90, v34, v90, v38
	v_fma_f32 v91, v35, v91, v39
	v_fma_f32 v92, v36, v92, v40
	v_cvt_pk_bf16_f32 v82, v82, v83
	v_cvt_pk_bf16_f32 v83, v84, v85
	v_cvt_pk_bf16_f32 v84, v90, v91
	v_cvt_pk_bf16_f32 v85, v92, v93
	global_store_dwordx4 v[86:87], v[82:85], off offset:1024 sc1
	v_mul_f32_e32 v90, v117, v127
	v_mul_f32_e32 v88, v88, v127
	v_mul_f32_e32 v82, v114, v127
	v_mul_f32_e32 v83, v115, v127
	v_mul_f32_e32 v84, v106, v127
	v_mul_f32_e32 v85, v116, v127
	v_fma_f32 v82, v26, v82, v30
	v_fma_f32 v83, v27, v83, v31
	v_fma_f32 v84, v28, v84, v32
	v_fma_f32 v85, v29, v85, v33
	v_mul_f32_e32 v91, v118, v127
	v_mul_f32_e32 v89, v89, v127
	v_fma_f32 v90, v18, v90, v22
	v_fma_f32 v88, v19, v88, v23
	v_fma_f32 v91, v20, v91, v24
	v_fma_f32 v89, v21, v89, v25
	v_cvt_pk_bf16_f32 v82, v82, v83
	v_cvt_pk_bf16_f32 v83, v84, v85
	v_cvt_pk_bf16_f32 v84, v90, v88
	v_cvt_pk_bf16_f32 v85, v91, v89
	global_store_dwordx4 v[86:87], v[82:85], off offset:2048 sc1
	v_mul_f32_e32 v88, v123, v127
	v_mul_f32_e32 v89, v124, v127
	v_mul_f32_e32 v82, v119, v127
	v_mul_f32_e32 v83, v120, v127
	v_mul_f32_e32 v84, v121, v127
	v_mul_f32_e32 v85, v122, v127
	v_fma_f32 v82, v10, v82, v14
	v_fma_f32 v83, v11, v83, v15
	v_fma_f32 v84, v12, v84, v16
	v_fma_f32 v85, v13, v85, v17
	v_mul_f32_e32 v90, v125, v127
	v_mul_f32_e32 v91, v126, v127
	s_add_u32 s8, s8, s10
	v_fma_f32 v88, v2, v88, v6
	v_fma_f32 v89, v3, v89, v7
	v_fma_f32 v90, v4, v90, v8
	v_fma_f32 v91, v5, v91, v9
	v_cvt_pk_bf16_f32 v82, v82, v83
	v_cvt_pk_bf16_f32 v83, v84, v85
	v_cvt_pk_bf16_f32 v84, v88, v89
	v_cvt_pk_bf16_f32 v85, v90, v91
	s_addc_u32 s9, s9, s11
	global_store_dwordx4 v[86:87], v[82:85], off offset:3072 sc1
	s_add_u32 s12, s12, s10
	s_waitcnt vmcnt(7)
	v_mov_b64_e32 v[96:97], v[68:69]
	s_waitcnt vmcnt(6)
	v_mov_b64_e32 v[92:93], v[72:73]
	s_waitcnt vmcnt(5)
	v_mov_b64_e32 v[88:89], v[76:77]
	s_waitcnt vmcnt(4)
	v_mov_b64_e32 v[84:85], v[80:81]
	s_addc_u32 s13, s13, s11
	s_andn2_b64 vcc, exec, s[14:15]
	v_mov_b64_e32 v[94:95], v[66:67]
	v_mov_b64_e32 v[90:91], v[70:71]
	v_mov_b64_e32 v[86:87], v[74:75]
	v_mov_b64_e32 v[82:83], v[78:79]
	s_cbranch_vccz .LBB0_3086

.LBB0_3088:
	v_lshlrev_b32_e32 v66, 12, v0
	v_or_b32_e32 v80, 0x200, v1
	v_and_b32_e32 v169, 0x30000, v66
	v_and_b32_e32 v66, 0x180, v1
	v_lshlrev_b32_e32 v173, 2, v66
	v_lshlrev_b32_e32 v66, 9, v80
	v_and_b32_e32 v174, 0x70000, v66
	s_movk_i32 s1, 0x380
	v_mov_b32_e32 v66, 0x200
	v_bitop3_b32 v66, v1, s1, v66 bitop3:0xc8
	v_lshlrev_b32_e32 v175, 2, v66
	v_lshlrev_b32_e32 v66, 9, v101
	s_ashr_i32 s1, s0, 31
	v_and_b32_e32 v176, 0xb0000, v66
	v_and_b32_e32 v66, 0x580, v101
	s_lshl_b64 s[4:5], s[0:1], 14
	v_readlane_b32 s6, v254, 58
	v_lshlrev_b32_e32 v178, 2, v66
	v_lshlrev_b32_e32 v66, 9, v100
	v_readlane_b32 s7, v254, 59
	s_add_u32 s4, s6, s4
	v_and_b32_e32 v212, 0xf0000, v66
	v_and_b32_e32 v66, 0x780, v100
	s_addc_u32 s5, s7, s5
	v_lshlrev_b32_e32 v170, 2, v1
	v_mov_b32_e32 v171, 0
	v_lshlrev_b32_e32 v213, 2, v66
	v_lshl_add_u64 v[66:67], s[4:5], 0, v[170:171]
	s_movk_i32 s12, 0x2000
	s_add_u32 s6, s4, 0x80000
	v_add_co_u32_e32 v68, vcc, s12, v66
	s_addc_u32 s7, s5, 0
	s_nop 0
	v_addc_co_u32_e32 v69, vcc, 0, v67, vcc
	v_lshl_add_u64 v[70:71], s[6:7], 0, v[170:171]
	global_load_dwordx4 v[180:183], v[68:69], off
	v_add_co_u32_e32 v72, vcc, s12, v70
	s_mov_b64 s[8:9], 0x2000
	s_nop 0
	v_addc_co_u32_e32 v73, vcc, 0, v71, vcc
	global_load_dwordx4 v[184:187], v[72:73], off
	global_load_dwordx4 v[114:117], v170, s[4:5] offset:16
	global_load_dwordx4 v[122:125], v170, s[4:5]
	s_mov_b64 s[10:11], 0x2800
	v_lshl_add_u64 v[72:73], v[66:67], 0, s[8:9]
	v_lshl_add_u64 v[66:67], v[66:67], 0, s[10:11]
	v_mov_b32_e32 v165, v171
	global_load_dwordx4 v[188:191], v[72:73], off offset:16
	global_load_dwordx4 v[98:101], v170, s[4:5] offset:2064
	global_load_dwordx4 v[106:109], v170, s[4:5] offset:2048
	global_load_dwordx4 v[196:199], v[68:69], off offset:2048
	global_load_dwordx4 v[200:203], v[66:67], off offset:16
	v_lshl_add_u64 v[66:67], s[4:5], 0, v[164:165]
	v_lshl_add_u64 v[68:69], v[66:67], 0, s[8:9]
	v_add_co_u32_e32 v66, vcc, s12, v66
	v_lshl_add_u64 v[70:71], v[70:71], 0, s[8:9]
	s_nop 0
	v_addc_co_u32_e32 v67, vcc, 0, v67, vcc
	global_load_dwordx4 v[82:85], v164, s[4:5] offset:16
	global_load_dwordx4 v[90:93], v164, s[4:5]
	global_load_dwordx4 v[154:157], v[66:67], off
	global_load_dwordx4 v[146:149], v[68:69], off offset:16
	s_nop 0
	global_load_dwordx4 v[66:69], v162, s[4:5] offset:16
	global_load_dwordx4 v[74:77], v162, s[4:5]
	global_load_dwordx4 v[192:195], v[70:71], off offset:16
	v_mov_b32_e32 v163, v171
	v_lshl_add_u64 v[72:73], s[4:5], 0, v[162:163]
	v_add_co_u32_e32 v70, vcc, s12, v72
	v_lshl_add_u64 v[78:79], v[72:73], 0, s[8:9]
	s_nop 0
	v_addc_co_u32_e32 v71, vcc, 0, v73, vcc
	global_load_dwordx4 v[138:141], v[70:71], off
	global_load_dwordx4 v[130:133], v[78:79], off offset:16
	global_load_dwordx4 v[118:121], v170, s[6:7] offset:16
	global_load_dwordx4 v[126:129], v170, s[6:7]
	v_lshlrev_b32_e32 v70, 2, v80
	v_mov_b32_e32 v71, v171
	v_lshl_add_u64 v[72:73], s[6:7], 0, v[70:71]
	global_load_dwordx4 v[102:105], v70, s[6:7] offset:16
	global_load_dwordx4 v[110:113], v70, s[6:7]
	v_lshl_add_u64 v[70:71], v[72:73], 0, s[8:9]
	v_add_co_u32_e32 v72, vcc, s12, v72
	v_lshl_add_u64 v[134:135], s[6:7], 0, v[162:163]
	s_nop 0
	v_addc_co_u32_e32 v73, vcc, 0, v73, vcc
	global_load_dwordx4 v[204:207], v[72:73], off
	global_load_dwordx4 v[208:211], v[70:71], off offset:16
	v_lshl_add_u64 v[70:71], s[6:7], 0, v[164:165]
	v_lshl_add_u64 v[72:73], v[70:71], 0, s[8:9]
	v_add_co_u32_e32 v70, vcc, s12, v70
	global_load_dwordx4 v[86:89], v164, s[6:7] offset:16
	global_load_dwordx4 v[94:97], v164, s[6:7]
	v_addc_co_u32_e32 v71, vcc, 0, v71, vcc
	global_load_dwordx4 v[158:161], v[70:71], off
	global_load_dwordx4 v[150:153], v[72:73], off offset:16
	v_lshl_add_u64 v[136:137], v[134:135], 0, s[8:9]
	v_add_co_u32_e32 v134, vcc, s12, v134
	v_readlane_b32 s44, v254, 18
	s_nop 0
	v_addc_co_u32_e32 v135, vcc, 0, v135, vcc
	v_readlane_b32 s54, v254, 28
	v_readlane_b32 s55, v254, 29
	global_load_dwordx4 v[70:73], v162, s[6:7] offset:16
	global_load_dwordx4 v[78:81], v162, s[6:7]
	global_load_dwordx4 v[142:145], v[134:135], off
	s_nop 0
	global_load_dwordx4 v[134:137], v[136:137], off offset:16
	v_readlane_b32 s56, v254, 30
	v_readlane_b32 s57, v254, 31
	global_load_dword v179, v169, s[54:55]
	s_nop 3
	global_load_dword v228, v173, s[56:57]
	global_load_dword v177, v174, s[54:55]
	global_load_dword v169, v175, s[56:57]
	s_nop 0
	global_load_dword v175, v176, s[54:55]
	global_load_dword v163, v178, s[56:57]
	global_load_dword v165, v212, s[54:55]
	global_load_dword v1, v213, s[56:57]
	s_lshl_b64 s[6:7], s[0:1], 13
	s_lshl_b64 s[0:1], s[0:1], 12
	v_readlane_b32 s4, v254, 60
	v_readlane_b32 s5, v254, 61
	s_add_u32 s4, s4, s0
	s_addc_u32 s5, s5, s1
	s_add_u32 s0, s92, s6
	s_addc_u32 s1, s93, s7
	s_add_u32 s0, s0, 0x4b68000
	s_addc_u32 s1, s1, 0
	v_readlane_b32 s45, v254, 19
	v_readlane_b32 s46, v254, 20
	v_readlane_b32 s47, v254, 21
	v_readlane_b32 s48, v254, 22
	v_readlane_b32 s49, v254, 23
	v_readlane_b32 s50, v254, 24
	v_readlane_b32 s51, v254, 25
	v_readlane_b32 s52, v254, 26
	v_readlane_b32 s53, v254, 27
	v_readlane_b32 s58, v254, 32
	s_waitcnt vmcnt(38)
	v_pk_add_f32 v[180:181], v[180:181], v[184:185]
	v_pk_add_f32 v[182:183], v[182:183], v[186:187]
	v_mul_f32_e32 v173, 0x3d372713, v180
	v_fma_f32 v173, v180, v173, 1.0
	v_mul_f32_e32 v174, 0x3d372713, v181
	v_mul_f32_e32 v173, v180, v173
	v_fma_f32 v174, v181, v174, 1.0
	v_mul_f32_e32 v173, 0x3fcc422a, v173
	v_mul_f32_e32 v174, v181, v174
	v_mul_f32_e32 v173, 0xbfb8aa3b, v173
	v_mul_f32_e32 v174, 0x3fcc422a, v174
	v_exp_f32_e32 v173, v173
	v_mul_f32_e32 v174, 0xbfb8aa3b, v174
	v_exp_f32_e32 v174, v174
	v_mul_f32_e32 v176, 0x3d372713, v183
	v_add_f32_e32 v173, 1.0, v173
	v_rcp_f32_e32 v184, v173
	v_add_f32_e32 v173, 1.0, v174
	v_mul_f32_e32 v174, 0x3d372713, v182
	v_fma_f32 v174, v182, v174, 1.0
	v_mul_f32_e32 v174, v182, v174
	v_fma_f32 v176, v183, v176, 1.0
	v_mul_f32_e32 v174, 0x3fcc422a, v174
	v_mul_f32_e32 v176, v183, v176
	v_mul_f32_e32 v174, 0xbfb8aa3b, v174
	v_mul_f32_e32 v176, 0x3fcc422a, v176
	v_exp_f32_e32 v174, v174
	v_mul_f32_e32 v176, 0xbfb8aa3b, v176
	v_exp_f32_e32 v176, v176
	v_rcp_f32_e32 v185, v173
	v_add_f32_e32 v173, 1.0, v174
	v_rcp_f32_e32 v186, v173
	v_add_f32_e32 v173, 1.0, v176
	s_waitcnt vmcnt(24)
	v_pk_add_f32 v[188:189], v[188:189], v[192:193]
	v_rcp_f32_e32 v187, v173
	v_mul_f32_e32 v173, 0x3d372713, v188
	v_fma_f32 v173, v188, v173, 1.0
	v_mul_f32_e32 v174, 0x3d372713, v189
	v_mul_f32_e32 v173, v188, v173
	v_fma_f32 v174, v189, v174, 1.0
	v_mul_f32_e32 v173, 0x3fcc422a, v173
	v_mul_f32_e32 v174, v189, v174
	v_mul_f32_e32 v173, 0xbfb8aa3b, v173
	v_mul_f32_e32 v174, 0x3fcc422a, v174
	v_exp_f32_e32 v173, v173
	v_mul_f32_e32 v174, 0xbfb8aa3b, v174
	v_exp_f32_e32 v174, v174
	v_pk_add_f32 v[190:191], v[190:191], v[194:195]
	v_add_f32_e32 v173, 1.0, v173
	v_rcp_f32_e32 v192, v173
	v_add_f32_e32 v173, 1.0, v174
	v_mul_f32_e32 v174, 0x3d372713, v190
	v_fma_f32 v174, v190, v174, 1.0
	v_mul_f32_e32 v176, 0x3d372713, v191
	v_mul_f32_e32 v174, v190, v174
	v_fma_f32 v176, v191, v176, 1.0
	v_mul_f32_e32 v174, 0x3fcc422a, v174
	v_mul_f32_e32 v176, v191, v176
	v_mul_f32_e32 v174, 0xbfb8aa3b, v174
	v_mul_f32_e32 v176, 0x3fcc422a, v176
	v_exp_f32_e32 v174, v174
	v_mul_f32_e32 v176, 0xbfb8aa3b, v176
	v_exp_f32_e32 v176, v176
	v_rcp_f32_e32 v193, v173
	v_add_f32_e32 v173, 1.0, v174
	v_rcp_f32_e32 v194, v173
	v_add_f32_e32 v173, 1.0, v176
	s_waitcnt vmcnt(17)
	v_pk_add_f32 v[196:197], v[196:197], v[204:205]
	v_rcp_f32_e32 v195, v173
	v_mul_f32_e32 v173, 0x3d372713, v196
	v_fma_f32 v173, v196, v173, 1.0
	v_mul_f32_e32 v174, 0x3d372713, v197
	v_mul_f32_e32 v173, v196, v173
	v_fma_f32 v174, v197, v174, 1.0
	v_mul_f32_e32 v173, 0x3fcc422a, v173
	v_mul_f32_e32 v174, v197, v174
	v_mul_f32_e32 v173, 0xbfb8aa3b, v173
	v_mul_f32_e32 v174, 0x3fcc422a, v174
	v_exp_f32_e32 v173, v173
	v_mul_f32_e32 v174, 0xbfb8aa3b, v174
	v_exp_f32_e32 v174, v174
	v_pk_add_f32 v[198:199], v[198:199], v[206:207]
	v_add_f32_e32 v173, 1.0, v173
	v_rcp_f32_e32 v204, v173
	v_add_f32_e32 v173, 1.0, v174
	v_mul_f32_e32 v174, 0x3d372713, v198
	v_fma_f32 v174, v198, v174, 1.0
	v_mul_f32_e32 v176, 0x3d372713, v199
	v_mul_f32_e32 v174, v198, v174
	v_fma_f32 v176, v199, v176, 1.0
	v_mul_f32_e32 v174, 0x3fcc422a, v174
	v_mul_f32_e32 v176, v199, v176
	v_mul_f32_e32 v174, 0xbfb8aa3b, v174
	v_mul_f32_e32 v176, 0x3fcc422a, v176
	v_exp_f32_e32 v174, v174
	v_mul_f32_e32 v176, 0xbfb8aa3b, v176
	v_exp_f32_e32 v176, v176
	v_rcp_f32_e32 v206, v173
	v_add_f32_e32 v173, 1.0, v174
	v_rcp_f32_e32 v207, v173
	v_add_f32_e32 v173, 1.0, v176
	v_pk_mov_b32 v[212:213], v[196:197], v[198:199] op_sel:[1,0]
	v_mov_b32_e32 v197, v199
	s_waitcnt vmcnt(16)
	v_pk_add_f32 v[198:199], v[200:201], v[208:209]
	v_rcp_f32_e32 v205, v173
	v_mul_f32_e32 v173, 0x3d372713, v198
	v_fma_f32 v173, v198, v173, 1.0
	v_mul_f32_e32 v173, v198, v173
	v_mul_f32_e32 v173, 0x3fcc422a, v173
	v_mul_f32_e32 v173, 0xbfb8aa3b, v173
	v_exp_f32_e32 v173, v173
	v_pk_mul_f32 v[196:197], v[196:197], v[204:205]
	v_pk_mul_f32 v[216:217], v[212:213], v[206:207]
	v_pk_fma_f32 v[200:201], v[212:213], v[206:207], v[196:197]
	v_add_f32_e32 v173, 1.0, v173
	v_pk_add_f32 v[206:207], v[200:201], v[200:201] op_sel:[0,1] op_sel_hi:[1,0]
	v_pk_add_f32 v[200:201], v[202:203], v[210:211]
	v_rcp_f32_e32 v202, v173
	v_mul_f32_e32 v173, 0x3d372713, v199
	s_waitcnt vmcnt(12)
	v_pk_add_f32 v[148:149], v[148:149], v[152:153]
	v_fma_f32 v173, v199, v173, 1.0
	v_mul_f32_e32 v174, 0x3d372713, v200
	v_mul_f32_e32 v152, 0x3d372713, v148
	v_mul_f32_e32 v173, v199, v173
	v_fma_f32 v174, v200, v174, 1.0
	v_fma_f32 v152, v148, v152, 1.0
	v_mul_f32_e32 v173, 0x3fcc422a, v173
	v_mul_f32_e32 v174, v200, v174
	v_pk_add_f32 v[146:147], v[146:147], v[150:151]
	v_mul_f32_e32 v152, v148, v152
	v_mul_f32_e32 v173, 0xbfb8aa3b, v173
	v_mul_f32_e32 v174, 0x3fcc422a, v174
	v_mul_f32_e32 v151, 0x3d372713, v147
	v_mul_f32_e32 v152, 0x3fcc422a, v152
	v_exp_f32_e32 v173, v173
	v_mul_f32_e32 v174, 0xbfb8aa3b, v174
	v_fma_f32 v151, v147, v151, 1.0
	v_mul_f32_e32 v152, 0xbfb8aa3b, v152
	v_exp_f32_e32 v174, v174
	v_mul_f32_e32 v150, 0x3d372713, v146
	v_mul_f32_e32 v151, v147, v151
	v_exp_f32_e32 v153, v152
	v_mul_f32_e32 v152, 0x3d372713, v149
	v_fma_f32 v150, v146, v150, 1.0
	v_mul_f32_e32 v151, 0x3fcc422a, v151
	v_fma_f32 v152, v149, v152, 1.0
	v_mul_f32_e32 v150, v146, v150
	v_mul_f32_e32 v151, 0xbfb8aa3b, v151
	v_mul_f32_e32 v152, v149, v152
	v_add_f32_e32 v173, 1.0, v173
	v_mul_f32_e32 v150, 0x3fcc422a, v150
	v_exp_f32_e32 v151, v151
	v_mul_f32_e32 v152, 0x3fcc422a, v152
	v_rcp_f32_e32 v203, v173
	v_add_f32_e32 v173, 1.0, v174
	v_mul_f32_e32 v150, 0xbfb8aa3b, v150
	v_mul_f32_e32 v152, 0xbfb8aa3b, v152
	v_rcp_f32_e32 v204, v173
	v_exp_f32_e32 v150, v150
	v_exp_f32_e32 v173, v152
	v_add_f32_e32 v151, 1.0, v151
	v_rcp_f32_e32 v152, v151
	v_add_f32_e32 v151, 1.0, v153
	v_add_f32_e32 v150, 1.0, v150
	v_rcp_f32_e32 v153, v151
	v_add_f32_e32 v151, 1.0, v173
	s_waitcnt vmcnt(9)
	v_pk_add_f32 v[138:139], v[138:139], v[142:143]
	v_rcp_f32_e32 v150, v150
	v_rcp_f32_e32 v151, v151
	v_mul_f32_e32 v142, 0x3d372713, v138
	v_fma_f32 v142, v138, v142, 1.0
	v_mul_f32_e32 v142, v138, v142
	v_pk_mov_b32 v[212:213], v[146:147], v[148:149] op_sel:[1,0]
	v_mov_b32_e32 v147, v149
	v_mul_f32_e32 v142, 0x3fcc422a, v142
	v_pk_mul_f32 v[146:147], v[146:147], v[150:151]
	v_mul_f32_e32 v142, 0xbfb8aa3b, v142
	v_exp_f32_e32 v150, v142
	v_pk_fma_f32 v[142:143], v[212:213], v[152:153], v[146:147]
	v_pk_add_f32 v[140:141], v[140:141], v[144:145]
	v_pk_add_f32 v[148:149], v[142:143], v[142:143] op_sel:[0,1] op_sel_hi:[1,0]
	v_mul_f32_e32 v143, 0x3d372713, v139
	v_fma_f32 v143, v139, v143, 1.0
	v_mul_f32_e32 v145, 0x3d372713, v141
	v_mul_f32_e32 v143, v139, v143
	v_mul_f32_e32 v144, 0x3d372713, v140
	v_fma_f32 v145, v141, v145, 1.0
	v_mul_f32_e32 v143, 0x3fcc422a, v143
	v_fma_f32 v144, v140, v144, 1.0
	v_mul_f32_e32 v145, v141, v145
	v_mul_f32_e32 v143, 0xbfb8aa3b, v143
	v_mul_f32_e32 v144, v140, v144
	v_mul_f32_e32 v145, 0x3fcc422a, v145
	v_exp_f32_e32 v143, v143
	v_mul_f32_e32 v144, 0x3fcc422a, v144
	v_mul_f32_e32 v145, 0xbfb8aa3b, v145
	v_mul_f32_e32 v144, 0xbfb8aa3b, v144
	v_exp_f32_e32 v145, v145
	v_exp_f32_e32 v144, v144
	v_add_f32_e32 v143, 1.0, v143
	v_add_f32_e32 v142, 1.0, v150
	v_rcp_f32_e32 v143, v143
	v_add_f32_e32 v145, 1.0, v145
	v_rcp_f32_e32 v142, v142
	v_add_f32_e32 v144, 1.0, v144
	v_rcp_f32_e32 v145, v145
	v_rcp_f32_e32 v144, v144
	v_mul_f32_e32 v150, v139, v143
	v_mbcnt_lo_u32_b32 v149, -1, 0
	v_pk_mul_f32 v[218:219], v[212:213], v[152:153]
	v_pk_fma_f32 v[150:151], v[138:139], v[142:143], v[150:151] op_sel_hi:[1,1,0]
	v_mul_f32_e32 v152, v141, v145
	v_mbcnt_hi_u32_b32 v149, -1, v149
	v_pk_fma_f32 v[152:153], v[140:141], v[144:145], v[152:153] op_sel_hi:[1,1,0]
	v_and_b32_e32 v151, 64, v149
	v_add_u32_e32 v151, 64, v151
	v_xor_b32_e32 v153, 1, v149
	s_waitcnt vmcnt(8)
	v_pk_add_f32 v[132:133], v[132:133], v[136:137]
	v_cmp_lt_i32_e32 vcc, v153, v151
	v_mul_f32_e32 v136, 0x3d372713, v132
	v_mul_f32_e32 v137, 0x3d372713, v133
	v_cndmask_b32_e32 v153, v149, v153, vcc
	v_fma_f32 v136, v132, v136, 1.0
	v_fma_f32 v137, v133, v137, 1.0
	v_lshlrev_b32_e32 v234, 2, v153
	v_xor_b32_e32 v153, 2, v149
	v_mul_f32_e32 v136, v132, v136
	v_mul_f32_e32 v137, v133, v137
	v_cmp_lt_i32_e32 vcc, v153, v151
	v_mul_f32_e32 v136, 0x3fcc422a, v136
	v_mul_f32_e32 v137, 0x3fcc422a, v137
	v_cndmask_b32_e32 v153, v149, v153, vcc
	v_mul_f32_e32 v136, 0xbfb8aa3b, v136
	v_mul_f32_e32 v137, 0xbfb8aa3b, v137
	v_lshlrev_b32_e32 v233, 2, v153
	v_xor_b32_e32 v153, 4, v149
	v_exp_f32_e32 v136, v136
	v_exp_f32_e32 v137, v137
	v_cmp_lt_i32_e32 vcc, v153, v151
	v_pk_add_f32 v[154:155], v[154:155], v[158:159]
	v_add_f32_e32 v136, 1.0, v136
	v_cndmask_b32_e32 v153, v149, v153, vcc
	v_lshlrev_b32_e32 v232, 2, v153
	v_xor_b32_e32 v153, 8, v149
	v_cmp_lt_i32_e32 vcc, v153, v151
	v_add_f32_e32 v137, 1.0, v137
	v_rcp_f32_e32 v136, v136
	v_cndmask_b32_e32 v153, v149, v153, vcc
	v_rcp_f32_e32 v137, v137
	v_lshlrev_b32_e32 v231, 2, v153
	v_xor_b32_e32 v153, 16, v149
	v_cmp_lt_i32_e32 vcc, v153, v151
	v_mul_f32_e32 v158, 0x3d372713, v154
	v_mul_f32_e32 v159, 0x3d372713, v155
	v_cndmask_b32_e32 v153, v149, v153, vcc
	v_lshlrev_b32_e32 v230, 2, v153
	v_xor_b32_e32 v153, 32, v149
	v_mul_f32_e32 v176, 0x3d372713, v201
	v_fma_f32 v158, v154, v158, 1.0
	v_fma_f32 v159, v155, v159, 1.0
	v_pk_add_f32 v[156:157], v[156:157], v[160:161]
	v_cmp_lt_i32_e32 vcc, v153, v151
	v_pk_mul_f32 v[220:221], v[132:133], v[136:137]
	v_fma_f32 v176, v201, v176, 1.0
	v_mul_f32_e32 v158, v154, v158
	v_mul_f32_e32 v159, v155, v159
	v_mul_f32_e32 v160, 0x3d372713, v156
	v_mul_f32_e32 v161, 0x3d372713, v157
	v_cndmask_b32_e32 v149, v149, v153, vcc
	v_mov_b32_e32 v151, v220
	v_mov_b32_e32 v153, v221
	v_mul_f32_e32 v176, v201, v176
	v_mul_f32_e32 v158, 0x3fcc422a, v158
	v_mul_f32_e32 v159, 0x3fcc422a, v159
	v_fma_f32 v160, v156, v160, 1.0
	v_fma_f32 v161, v157, v161, 1.0
	v_pk_mul_f32 v[212:213], v[180:181], v[184:185]
	v_pk_add_f32 v[224:225], v[150:151], v[152:153]
	v_pk_mul_f32 v[150:151], v[188:189], v[192:193]
	v_mul_f32_e32 v176, 0x3fcc422a, v176
	v_mul_f32_e32 v158, 0xbfb8aa3b, v158
	v_mul_f32_e32 v159, 0xbfb8aa3b, v159
	v_mul_f32_e32 v160, v156, v160
	v_mul_f32_e32 v161, v157, v161
	v_mov_b32_e32 v152, v212
	v_mov_b32_e32 v153, v150
	v_mov_b32_e32 v150, v213
	v_mul_f32_e32 v176, 0xbfb8aa3b, v176
	v_exp_f32_e32 v158, v158
	v_exp_f32_e32 v159, v159
	v_mul_f32_e32 v160, 0x3fcc422a, v160
	v_mul_f32_e32 v161, 0x3fcc422a, v161
	v_pk_add_f32 v[130:131], v[130:131], v[134:135]
	v_pk_mul_f32 v[214:215], v[182:183], v[186:187]
	v_pk_add_f32 v[150:151], v[152:153], v[150:151]
	v_pk_mul_f32 v[152:153], v[190:191], v[194:195]
	v_exp_f32_e32 v176, v176
	v_mul_f32_e32 v160, 0xbfb8aa3b, v160
	v_mul_f32_e32 v161, 0xbfb8aa3b, v161
	v_mul_f32_e32 v134, 0x3d372713, v130
	v_mul_f32_e32 v135, 0x3d372713, v131
	v_mov_b32_e32 v212, v214
	v_mov_b32_e32 v213, v152
	v_mov_b32_e32 v152, v215
	v_exp_f32_e32 v160, v160
	v_exp_f32_e32 v161, v161
	v_fma_f32 v134, v130, v134, 1.0
	v_fma_f32 v135, v131, v135, 1.0
	v_pk_add_f32 v[152:153], v[212:213], v[152:153]
	v_mul_f32_e32 v134, v130, v134
	v_mul_f32_e32 v135, v131, v135
	v_pk_add_f32 v[150:151], v[150:151], v[152:153]
	v_add_f32_e32 v158, 1.0, v158
	v_add_f32_e32 v159, 1.0, v159
	v_mul_f32_e32 v134, 0x3fcc422a, v134
	v_mul_f32_e32 v135, 0x3fcc422a, v135
	v_lshlrev_b32_e32 v229, 2, v149
	v_add_f32_e32 v149, 0, v150
	v_pk_add_f32 v[100:101], v[100:101], v[104:105]
	v_add_f32_e32 v174, 1.0, v176
	v_rcp_f32_e32 v158, v158
	v_rcp_f32_e32 v159, v159
	v_mul_f32_e32 v134, 0xbfb8aa3b, v134
	v_mul_f32_e32 v135, 0xbfb8aa3b, v135
	v_add_f32_e32 v236, v149, v151
	v_mul_f32_e32 v149, 0x3d372713, v100
	v_rcp_f32_e32 v205, v174
	v_add_f32_e32 v160, 1.0, v160
	v_add_f32_e32 v161, 1.0, v161
	v_exp_f32_e32 v134, v134
	v_exp_f32_e32 v135, v135
	v_mov_b32_e32 v173, v171
	v_fma_f32 v149, v100, v149, 1.0
	v_mul_f32_e32 v171, 0x3d372713, v101
	v_rcp_f32_e32 v160, v160
	v_rcp_f32_e32 v161, v161
	v_mul_f32_e32 v149, v100, v149
	v_fma_f32 v171, v101, v171, 1.0
	v_mul_f32_e32 v149, 0x3fcc422a, v149
	v_mul_f32_e32 v171, v101, v171
	v_mul_f32_e32 v174, v199, v203
	v_mul_f32_e32 v149, 0xbfb8aa3b, v149
	v_mul_f32_e32 v171, 0x3fcc422a, v171
	v_pk_mul_f32 v[238:239], v[154:155], v[158:159]
	s_waitcnt vmcnt(3)
	v_pk_fma_f32 v[208:209], v[198:199], v[202:203], v[174:175] op_sel_hi:[1,1,0]
	v_mul_f32_e32 v174, v201, v205
	v_add_f32_e32 v134, 1.0, v134
	v_add_f32_e32 v135, 1.0, v135
	v_exp_f32_e32 v149, v149
	v_mul_f32_e32 v171, 0xbfb8aa3b, v171
	v_mov_b32_e32 v207, v239
	v_mov_b32_e32 v237, v238
	v_pk_fma_f32 v[210:211], v[200:201], v[204:205], v[174:175] op_sel_hi:[1,1,0]
	v_rcp_f32_e32 v134, v134
	v_rcp_f32_e32 v135, v135
	v_exp_f32_e32 v171, v171
	v_pk_add_f32 v[206:207], v[236:237], v[206:207]
	v_pk_mul_f32 v[236:237], v[156:157], v[160:161]
	v_pk_add_f32 v[90:91], v[90:91], v[94:95]
	v_mov_b32_e32 v209, v236
	v_mov_b32_e32 v211, v237
	v_pk_add_f32 v[208:209], v[208:209], v[210:211]
	v_add_f32_e32 v149, 1.0, v149
	v_pk_add_f32 v[206:207], v[206:207], v[208:209]
	v_mul_f32_e32 v94, 0x3d372713, v90
	v_rcp_f32_e32 v222, v149
	v_add_f32_e32 v149, 1.0, v171
	v_pk_add_f32 v[206:207], v[206:207], v[206:207] op_sel:[0,1] op_sel_hi:[1,0]
	v_fma_f32 v94, v90, v94, 1.0
	v_mul_f32_e32 v95, 0x3d372713, v91
	v_pk_add_f32 v[92:93], v[92:93], v[96:97]
	v_pk_mul_f32 v[96:97], v[130:131], v[134:135]
	v_rcp_f32_e32 v220, v149
	v_mul_f32_e32 v94, v90, v94
	v_fma_f32 v95, v91, v95, 1.0
	v_mov_b32_e32 v149, v97
	v_mov_b32_e32 v207, v96
	v_mul_f32_e32 v94, 0x3fcc422a, v94
	v_mul_f32_e32 v95, v91, v95
	v_pk_add_f32 v[96:97], v[206:207], v[148:149]
	v_mul_f32_e32 v94, 0xbfb8aa3b, v94
	v_mul_f32_e32 v95, 0x3fcc422a, v95
	v_pk_add_f32 v[96:97], v[96:97], v[224:225]
	v_exp_f32_e32 v94, v94
	v_mul_f32_e32 v95, 0xbfb8aa3b, v95
	v_add_f32_e32 v96, v96, v97
	v_exp_f32_e32 v95, v95
	ds_bpermute_b32 v97, v234, v96
	v_add_f32_e32 v94, 1.0, v94
	v_rcp_f32_e32 v174, v94
	v_add_f32_e32 v94, 1.0, v95
	v_mul_f32_e32 v95, 0x3d372713, v92
	v_fma_f32 v95, v92, v95, 1.0
	s_waitcnt lgkmcnt(0)
	v_add_f32_e32 v96, v96, v97
	v_mul_f32_e32 v95, v92, v95
	ds_bpermute_b32 v97, v233, v96
	v_mul_f32_e32 v95, 0x3fcc422a, v95
	v_mul_f32_e32 v95, 0xbfb8aa3b, v95
	v_mul_f32_e32 v149, 0x3d372713, v93
	v_exp_f32_e32 v171, v95
	v_fma_f32 v149, v93, v149, 1.0
	v_mul_f32_e32 v149, v93, v149
	v_mul_f32_e32 v149, 0x3fcc422a, v149
	s_waitcnt lgkmcnt(0)
	v_add_f32_e32 v97, v96, v97
	v_mul_f32_e32 v149, 0xbfb8aa3b, v149
	ds_bpermute_b32 v206, v232, v97
	v_add_f32_e32 v148, 1.0, v171
	v_exp_f32_e32 v171, v149
	v_pk_add_f32 v[86:87], v[82:83], v[86:87]
	v_mov_b32_e32 v226, v196
	v_mul_f32_e32 v82, 0x3d372713, v86
	v_add_f32_e32 v96, 1.0, v171
	s_waitcnt lgkmcnt(0)
	v_add_f32_e32 v171, v97, v206
	ds_bpermute_b32 v206, v231, v171
	v_fma_f32 v82, v86, v82, 1.0
	v_mul_f32_e32 v82, v86, v82
	v_mul_f32_e32 v82, 0x3fcc422a, v82
	v_mul_f32_e32 v82, 0xbfb8aa3b, v82
	s_waitcnt lgkmcnt(0)
	v_add_f32_e32 v83, v171, v206
	ds_bpermute_b32 v171, v230, v83
	v_exp_f32_e32 v82, v82
	v_mov_b32_e32 v227, v216
	v_mov_b32_e32 v208, v146
	v_mov_b32_e32 v209, v218
	s_waitcnt lgkmcnt(0)
	v_add_f32_e32 v83, v83, v171
	ds_bpermute_b32 v171, v229, v83
	v_add_f32_e32 v82, 1.0, v82
	v_rcp_f32_e32 v206, v82
	v_mov_b32_e32 v146, v219
	v_mov_b32_e32 v196, v217
	s_waitcnt lgkmcnt(0)
	v_add_f32_e32 v82, v83, v171
	v_mul_f32_e32 v210, 0x3a000000, v82
	v_pk_fma_f32 v[180:181], v[180:181], v[184:185], v[210:211] op_sel_hi:[1,1,0] neg_lo:[0,0,1] neg_hi:[0,0,1]
	v_pk_fma_f32 v[182:183], v[182:183], v[186:187], v[210:211] op_sel_hi:[1,1,0] neg_lo:[0,0,1] neg_hi:[0,0,1]
	v_pk_mul_f32 v[184:185], v[180:181], v[180:181]
	v_pk_mul_f32 v[186:187], v[182:183], v[182:183]
	v_pk_fma_f32 v[82:83], v[132:133], v[136:137], v[210:211] op_sel_hi:[1,1,0] neg_lo:[0,0,1] neg_hi:[0,0,1]
	v_pk_fma_f32 v[132:133], v[138:139], v[142:143], v[210:211] op_sel_hi:[1,1,0] neg_lo:[0,0,1] neg_hi:[0,0,1]
	v_add_f32_e32 v142, v184, v185
	v_pk_fma_f32 v[188:189], v[188:189], v[192:193], v[210:211] op_sel_hi:[1,1,0] neg_lo:[0,0,1] neg_hi:[0,0,1]
	v_add_f32_e32 v142, v186, v142
	v_pk_mul_f32 v[192:193], v[188:189], v[188:189]
	v_add_f32_e32 v142, v187, v142
	v_pk_fma_f32 v[190:191], v[190:191], v[194:195], v[210:211] op_sel_hi:[1,1,0] neg_lo:[0,0,1] neg_hi:[0,0,1]
	v_add_f32_e32 v142, v192, v142
	v_pk_mul_f32 v[194:195], v[190:191], v[190:191]
	v_add_f32_e32 v142, v193, v142
	v_pk_add_f32 v[218:219], v[226:227], v[210:211] op_sel_hi:[1,0] neg_lo:[0,1] neg_hi:[0,1]
	v_add_f32_e32 v142, v194, v142
	v_pk_mul_f32 v[224:225], v[218:219], v[218:219]
	v_add_f32_e32 v142, v195, v142
	v_pk_add_f32 v[196:197], v[196:197], v[210:211] op_sel_hi:[1,0] neg_lo:[0,1] neg_hi:[0,1]
	v_add_f32_e32 v142, v224, v142
	v_pk_mul_f32 v[226:227], v[196:197], v[196:197]
	v_add_f32_e32 v142, v225, v142
	v_pk_fma_f32 v[198:199], v[198:199], v[202:203], v[210:211] op_sel_hi:[1,1,0] neg_lo:[0,0,1] neg_hi:[0,0,1]
	v_add_f32_e32 v142, v226, v142
	v_pk_mul_f32 v[202:203], v[198:199], v[198:199]
	v_add_f32_e32 v142, v227, v142
	v_pk_fma_f32 v[200:201], v[200:201], v[204:205], v[210:211] op_sel_hi:[1,1,0] neg_lo:[0,0,1] neg_hi:[0,0,1]
	v_add_f32_e32 v142, v202, v142
	v_pk_mul_f32 v[204:205], v[200:201], v[200:201]
	v_add_f32_e32 v142, v203, v142
	v_pk_fma_f32 v[154:155], v[154:155], v[158:159], v[210:211] op_sel_hi:[1,1,0] neg_lo:[0,0,1] neg_hi:[0,0,1]
	v_add_f32_e32 v142, v204, v142
	v_pk_mul_f32 v[158:159], v[154:155], v[154:155]
	v_add_f32_e32 v142, v205, v142
	v_pk_fma_f32 v[156:157], v[156:157], v[160:161], v[210:211] op_sel_hi:[1,1,0] neg_lo:[0,0,1] neg_hi:[0,0,1]
	v_add_f32_e32 v142, v158, v142
	v_pk_mul_f32 v[160:161], v[156:157], v[156:157]
	v_add_f32_e32 v142, v159, v142
	v_pk_add_f32 v[208:209], v[208:209], v[210:211] op_sel_hi:[1,0] neg_lo:[0,1] neg_hi:[0,1]
	v_add_f32_e32 v142, v160, v142
	v_pk_mul_f32 v[236:237], v[208:209], v[208:209]
	v_add_f32_e32 v142, v161, v142
	v_pk_add_f32 v[146:147], v[146:147], v[210:211] op_sel_hi:[1,0] neg_lo:[0,1] neg_hi:[0,1]
	v_add_f32_e32 v142, v236, v142
	v_pk_mul_f32 v[238:239], v[146:147], v[146:147]
	v_add_f32_e32 v142, v237, v142
	v_add_f32_e32 v142, v238, v142
	v_pk_mul_f32 v[138:139], v[132:133], v[132:133]
	v_add_f32_e32 v142, v239, v142
	v_pk_add_f32 v[88:89], v[84:85], v[88:89]
	v_pk_fma_f32 v[84:85], v[130:131], v[134:135], v[210:211] op_sel_hi:[1,1,0] neg_lo:[0,0,1] neg_hi:[0,0,1]
	v_pk_fma_f32 v[130:131], v[140:141], v[144:145], v[210:211] op_sel_hi:[1,1,0] neg_lo:[0,0,1] neg_hi:[0,0,1]
	v_add_f32_e32 v138, v138, v142
	v_pk_mul_f32 v[140:141], v[130:131], v[130:131]
	v_add_f32_e32 v138, v139, v138
	v_add_f32_e32 v138, v140, v138
	v_pk_mul_f32 v[134:135], v[84:85], v[84:85]
	v_add_f32_e32 v138, v141, v138
	v_add_f32_e32 v134, v134, v138
	v_pk_mul_f32 v[136:137], v[82:83], v[82:83]
	v_add_f32_e32 v134, v135, v134
	v_add_f32_e32 v134, v136, v134
	v_add_f32_e32 v134, v137, v134
	ds_bpermute_b32 v135, v234, v134
	v_pk_add_f32 v[122:123], v[122:123], v[126:127]
	v_mul_f32_e32 v140, 0x3d372713, v89
	v_mul_f32_e32 v126, 0x3d372713, v122
	v_fma_f32 v140, v89, v140, 1.0
	s_waitcnt lgkmcnt(0)
	v_add_f32_e32 v134, v134, v135
	ds_bpermute_b32 v135, v233, v134
	v_fma_f32 v126, v122, v126, 1.0
	v_mul_f32_e32 v140, v89, v140
	v_mul_f32_e32 v126, v122, v126
	v_mul_f32_e32 v127, 0x3d372713, v123
	s_waitcnt lgkmcnt(0)
	v_add_f32_e32 v134, v134, v135
	ds_bpermute_b32 v135, v232, v134
	v_mul_f32_e32 v140, 0x3fcc422a, v140
	v_mul_f32_e32 v126, 0x3fcc422a, v126
	v_fma_f32 v127, v123, v127, 1.0
	v_mul_f32_e32 v140, 0xbfb8aa3b, v140
	s_waitcnt lgkmcnt(0)
	v_add_f32_e32 v138, v134, v135
	ds_bpermute_b32 v139, v231, v138
	v_mul_f32_e32 v126, 0xbfb8aa3b, v126
	v_mul_f32_e32 v127, v123, v127
	v_pk_add_f32 v[124:125], v[124:125], v[128:129]
	v_pk_add_f32 v[118:119], v[114:115], v[118:119]
	s_waitcnt lgkmcnt(0)
	v_add_f32_e32 v138, v138, v139
	ds_bpermute_b32 v139, v230, v138
	v_exp_f32_e32 v140, v140
	v_exp_f32_e32 v126, v126
	v_mul_f32_e32 v127, 0x3fcc422a, v127
	v_mul_f32_e32 v128, 0x3d372713, v124
	s_waitcnt lgkmcnt(0)
	v_add_f32_e32 v138, v138, v139
	ds_bpermute_b32 v139, v229, v138
	v_mul_f32_e32 v114, 0x3d372713, v118
	v_mul_f32_e32 v127, 0xbfb8aa3b, v127
	v_fma_f32 v128, v124, v128, 1.0
	v_fma_f32 v114, v118, v114, 1.0
	s_waitcnt lgkmcnt(0)
	v_add_f32_e32 v138, v138, v139
	v_mov_b32_e32 v139, 0x358637bd
	v_fmac_f32_e32 v139, 0x3a000000, v138
	v_rsq_f32_e32 v138, v139
	v_mul_f32_e32 v115, 0x3d372713, v119
	v_exp_f32_e32 v127, v127
	v_mul_f32_e32 v128, v124, v128
	v_mul_f32_e32 v129, 0x3d372713, v125
	v_mul_f32_e32 v114, v118, v114
	v_fma_f32 v115, v119, v115, 1.0
	v_mul_f32_e32 v128, 0x3fcc422a, v128
	v_fma_f32 v129, v125, v129, 1.0
	v_mul_f32_e32 v114, 0x3fcc422a, v114
	v_mul_f32_e32 v115, v119, v115
	v_add_f32_e32 v139, 1.0, v140
	v_add_f32_e32 v126, 1.0, v126
	v_mul_f32_e32 v128, 0xbfb8aa3b, v128
	v_mul_f32_e32 v129, v125, v129
	v_mul_f32_e32 v114, 0xbfb8aa3b, v114
	v_mul_f32_e32 v115, 0x3fcc422a, v115
	v_pk_mul_f32 v[142:143], v[180:181], v[138:139] op_sel_hi:[1,0]
	v_rcp_f32_e32 v178, v126
	v_exp_f32_e32 v128, v128
	v_mul_f32_e32 v129, 0x3fcc422a, v129
	v_exp_f32_e32 v114, v114
	v_mul_f32_e32 v115, 0xbfb8aa3b, v115
	v_pk_fma_f32 v[58:59], v[58:59], v[142:143], v[62:63]
	v_pk_mul_f32 v[62:63], v[182:183], v[138:139] op_sel_hi:[1,0]
	v_add_f32_e32 v126, 1.0, v127
	v_mul_f32_e32 v129, 0xbfb8aa3b, v129
	v_exp_f32_e32 v115, v115
	v_pk_fma_f32 v[60:61], v[60:61], v[62:63], v[64:65]
	v_pk_mul_f32 v[62:63], v[188:189], v[138:139] op_sel_hi:[1,0]
	v_rcp_f32_e32 v126, v126
	v_exp_f32_e32 v129, v129
	v_pk_fma_f32 v[50:51], v[50:51], v[62:63], v[54:55]
	v_pk_mul_f32 v[54:55], v[190:191], v[138:139] op_sel_hi:[1,0]
	v_add_f32_e32 v128, 1.0, v128
	v_pk_fma_f32 v[52:53], v[52:53], v[54:55], v[56:57]
	v_mov_b32_e32 v54, v122
	v_mov_b32_e32 v55, v58
	v_add_f32_e32 v114, 1.0, v114
	v_pk_mul_f32 v[54:55], v[54:55], v[178:179]
	v_mov_b32_e32 v127, v179
	v_rcp_f32_e32 v150, v128
	v_pk_add_f32 v[116:117], v[116:117], v[120:121]
	v_rcp_f32_e32 v152, v114
	v_add_f32_e32 v114, 1.0, v115
	global_store_dwordx4 v170, v[58:61], s[0:1] sc1
	v_add_f32_e32 v55, v228, v55
	v_add_f32_e32 v128, 1.0, v129
	v_mov_b32_e32 v58, v123
	v_rcp_f32_e32 v120, v114
	v_mul_f32_e32 v114, 0x3d372713, v116
	v_mul_f32_e32 v56, v54, v55
	v_pk_mul_f32 v[54:55], v[58:59], v[126:127]
	v_rcp_f32_e32 v128, v128
	v_fma_f32 v114, v116, v114, 1.0
	v_add_f32_e32 v55, v228, v55
	v_mov_b32_e32 v151, v179
	v_mul_f32_e32 v114, v116, v114
	v_mul_f32_e32 v115, 0x3d372713, v117
	v_mul_f32_e32 v57, v54, v55
	v_mov_b32_e32 v54, v124
	v_mov_b32_e32 v55, v60
	v_mul_f32_e32 v114, 0x3fcc422a, v114
	v_fma_f32 v115, v117, v115, 1.0
	v_pk_mul_f32 v[54:55], v[54:55], v[150:151]
	v_mov_b32_e32 v129, v179
	v_mul_f32_e32 v114, 0xbfb8aa3b, v114
	v_mul_f32_e32 v115, v117, v115
	v_add_f32_e32 v55, v228, v55
	v_mov_b32_e32 v60, v125
	v_exp_f32_e32 v114, v114
	v_mul_f32_e32 v115, 0x3fcc422a, v115
	v_mul_f32_e32 v58, v54, v55
	v_pk_mul_f32 v[54:55], v[60:61], v[128:129]
	v_mul_f32_e32 v115, 0xbfb8aa3b, v115
	v_add_f32_e32 v55, v228, v55
	v_mov_b32_e32 v153, v179
	v_exp_f32_e32 v115, v115
	v_mul_f32_e32 v59, v54, v55
	v_mov_b32_e32 v54, v118
	v_mov_b32_e32 v55, v50
	v_pk_mul_f32 v[54:55], v[54:55], v[152:153]
	v_add_f32_e32 v114, 1.0, v114
	global_store_dwordx4 v170, v[50:53], s[0:1] offset:16 sc1
	v_mov_b32_e32 v121, v179
	v_rcp_f32_e32 v214, v114
	v_add_f32_e32 v50, v228, v55
	v_pk_add_f32 v[106:107], v[106:107], v[110:111]
	v_mul_f32_e32 v54, v54, v50
	v_mov_b32_e32 v50, v119
	v_add_f32_e32 v114, 1.0, v115
	v_mul_f32_e32 v110, 0x3d372713, v106
	v_pk_mul_f32 v[50:51], v[50:51], v[120:121]
	v_rcp_f32_e32 v212, v114
	v_fma_f32 v110, v106, v110, 1.0
	v_add_f32_e32 v51, v228, v51
	v_mov_b32_e32 v215, v179
	v_mul_f32_e32 v110, v106, v110
	v_mul_f32_e32 v111, 0x3d372713, v107
	v_mul_f32_e32 v55, v50, v51
	v_mov_b32_e32 v50, v116
	v_mov_b32_e32 v51, v52
	v_mul_f32_e32 v110, 0x3fcc422a, v110
	v_fma_f32 v111, v107, v111, 1.0
	v_pk_mul_f32 v[50:51], v[50:51], v[214:215]
	v_mov_b32_e32 v213, v179
	v_mul_f32_e32 v110, 0xbfb8aa3b, v110
	v_mul_f32_e32 v111, v107, v111
	v_pk_add_f32 v[108:109], v[108:109], v[112:113]
	v_add_f32_e32 v51, v228, v51
	v_mov_b32_e32 v52, v117
	v_lshl_add_u64 v[172:173], s[4:5], 0, v[172:173]
	s_mov_b64 s[4:5], 0x2000000
	v_exp_f32_e32 v110, v110
	v_mul_f32_e32 v111, 0x3fcc422a, v111
	v_mul_f32_e32 v112, 0x3d372713, v108
	v_mul_f32_e32 v60, v50, v51
	v_pk_mul_f32 v[50:51], v[52:53], v[212:213]
	v_lshl_add_u64 v[114:115], v[172:173], 0, s[4:5]
	v_mul_f32_e32 v111, 0xbfb8aa3b, v111
	v_fma_f32 v112, v108, v112, 1.0
	v_add_f32_e32 v51, v228, v51
	s_brev_b32 s4, 64
	v_exp_f32_e32 v111, v111
	v_mul_f32_e32 v112, v108, v112
	v_mul_f32_e32 v113, 0x3d372713, v109
	v_mul_f32_e32 v53, v50, v51
	v_cvt_pk_bf16_f32 v50, v56, v57
	v_cvt_pk_bf16_f32 v51, v58, v59
	v_cvt_pk_bf16_f32 v52, v54, v55
	v_add_co_u32_e32 v54, vcc, s4, v172
	v_mul_f32_e32 v112, 0x3fcc422a, v112
	v_fma_f32 v113, v109, v113, 1.0
	v_addc_co_u32_e32 v55, vcc, 0, v173, vcc
	v_add_f32_e32 v110, 1.0, v110
	v_mul_f32_e32 v112, 0xbfb8aa3b, v112
	v_mul_f32_e32 v113, v109, v113
	v_pk_add_f32 v[98:99], v[98:99], v[102:103]
	v_cvt_pk_bf16_f32 v53, v60, v53
	global_store_dwordx4 v[54:55], v[50:53], off sc1
	v_rcp_f32_e32 v176, v110
	v_exp_f32_e32 v112, v112
	v_pk_mul_f32 v[50:51], v[218:219], v[138:139] op_sel_hi:[1,0]
	v_mul_f32_e32 v113, 0x3fcc422a, v113
	v_mul_f32_e32 v102, 0x3d372713, v98
	v_pk_fma_f32 v[42:43], v[42:43], v[50:51], v[46:47]
	v_pk_mul_f32 v[46:47], v[196:197], v[138:139] op_sel_hi:[1,0]
	v_add_f32_e32 v110, 1.0, v111
	v_mul_f32_e32 v113, 0xbfb8aa3b, v113
	v_fma_f32 v102, v98, v102, 1.0
	v_pk_fma_f32 v[44:45], v[44:45], v[46:47], v[48:49]
	v_pk_mul_f32 v[46:47], v[198:199], v[138:139] op_sel_hi:[1,0]
	v_rcp_f32_e32 v110, v110
	v_exp_f32_e32 v113, v113
	v_mul_f32_e32 v102, v98, v102
	v_pk_fma_f32 v[34:35], v[34:35], v[46:47], v[38:39]
	v_pk_mul_f32 v[38:39], v[200:201], v[138:139] op_sel_hi:[1,0]
	v_mul_f32_e32 v102, 0x3fcc422a, v102
	v_mul_f32_e32 v103, 0x3d372713, v99
	v_pk_fma_f32 v[36:37], v[36:37], v[38:39], v[40:41]
	v_mov_b32_e32 v38, v106
	v_mov_b32_e32 v39, v42
	v_add_f32_e32 v112, 1.0, v112
	v_mul_f32_e32 v102, 0xbfb8aa3b, v102
	v_fma_f32 v103, v99, v103, 1.0
	v_pk_mul_f32 v[38:39], v[38:39], v[176:177]
	v_mov_b32_e32 v111, v177
	v_rcp_f32_e32 v216, v112
	v_exp_f32_e32 v102, v102
	v_mul_f32_e32 v103, v99, v103
	global_store_dwordx4 v170, v[42:45], s[0:1] offset:2048 sc1
	v_add_f32_e32 v39, v169, v39
	v_add_f32_e32 v112, 1.0, v113
	v_mov_b32_e32 v42, v107
	v_mul_f32_e32 v103, 0x3fcc422a, v103
	v_mul_f32_e32 v40, v38, v39
	v_pk_mul_f32 v[38:39], v[42:43], v[110:111]
	v_rcp_f32_e32 v112, v112
	v_mul_f32_e32 v103, 0xbfb8aa3b, v103
	v_add_f32_e32 v39, v169, v39
	v_mov_b32_e32 v217, v177
	v_exp_f32_e32 v103, v103
	v_mul_f32_e32 v41, v38, v39
	v_mov_b32_e32 v38, v108
	v_mov_b32_e32 v39, v44
	v_add_f32_e32 v102, 1.0, v102
	v_pk_mul_f32 v[38:39], v[38:39], v[216:217]
	v_mov_b32_e32 v113, v177
	v_rcp_f32_e32 v104, v102
	v_add_f32_e32 v39, v169, v39
	v_mov_b32_e32 v44, v109
	v_mul_f32_e32 v42, v38, v39
	v_pk_mul_f32 v[38:39], v[44:45], v[112:113]
	v_add_f32_e32 v102, 1.0, v103
	v_add_f32_e32 v39, v169, v39
	v_mov_b32_e32 v105, v177
	v_rcp_f32_e32 v102, v102
	v_mul_f32_e32 v43, v38, v39
	v_mov_b32_e32 v38, v98
	v_mov_b32_e32 v39, v34
	v_pk_mul_f32 v[38:39], v[38:39], v[104:105]
	global_store_dwordx4 v170, v[34:37], s[0:1] offset:2064 sc1
	v_mov_b32_e32 v103, v177
	v_mov_b32_e32 v223, v177
	v_add_f32_e32 v34, v169, v39
	v_mul_f32_e32 v38, v38, v34
	v_mov_b32_e32 v34, v99
	v_pk_mul_f32 v[34:35], v[34:35], v[102:103]
	v_mov_b32_e32 v221, v177
	v_add_f32_e32 v35, v169, v35
	v_mul_f32_e32 v39, v34, v35
	v_mov_b32_e32 v34, v100
	v_mov_b32_e32 v35, v36
	v_pk_mul_f32 v[34:35], v[34:35], v[222:223]
	v_mov_b32_e32 v36, v101
	v_add_f32_e32 v35, v169, v35
	v_mul_f32_e32 v44, v34, v35
	v_pk_mul_f32 v[34:35], v[36:37], v[220:221]
	v_rcp_f32_e32 v94, v94
	v_add_f32_e32 v35, v169, v35
	v_mul_f32_e32 v37, v34, v35
	v_cvt_pk_bf16_f32 v34, v40, v41
	v_cvt_pk_bf16_f32 v35, v42, v43
	v_cvt_pk_bf16_f32 v36, v38, v39
	v_cvt_pk_bf16_f32 v37, v44, v37
	global_store_dwordx4 v[114:115], v[34:37], off offset:1024 sc1
	v_mul_f32_e32 v136, 0x3d372713, v87
	v_fma_f32 v136, v87, v136, 1.0
	v_pk_mul_f32 v[34:35], v[154:155], v[138:139] op_sel_hi:[1,0]
	v_mov_b32_e32 v95, v175
	v_pk_fma_f32 v[26:27], v[26:27], v[34:35], v[30:31]
	v_pk_mul_f32 v[30:31], v[156:157], v[138:139] op_sel_hi:[1,0]
	v_rcp_f32_e32 v148, v148
	v_pk_fma_f32 v[28:29], v[28:29], v[30:31], v[32:33]
	v_pk_mul_f32 v[30:31], v[208:209], v[138:139] op_sel_hi:[1,0]
	v_mul_f32_e32 v136, v87, v136
	v_pk_fma_f32 v[18:19], v[18:19], v[30:31], v[22:23]
	v_pk_mul_f32 v[22:23], v[146:147], v[138:139] op_sel_hi:[1,0]
	global_store_dwordx4 v164, v[26:29], s[0:1] sc1
	v_pk_fma_f32 v[20:21], v[20:21], v[22:23], v[24:25]
	v_mov_b32_e32 v22, v90
	v_mov_b32_e32 v23, v26
	v_pk_mul_f32 v[22:23], v[22:23], v[174:175]
	v_mov_b32_e32 v26, v91
	s_waitcnt vmcnt(9)
	v_add_f32_e32 v23, v163, v23
	v_mul_f32_e32 v136, 0x3fcc422a, v136
	v_mul_f32_e32 v137, 0x3d372713, v88
	v_mul_f32_e32 v24, v22, v23
	v_pk_mul_f32 v[22:23], v[26:27], v[94:95]
	v_rcp_f32_e32 v96, v96
	v_mul_f32_e32 v136, 0xbfb8aa3b, v136
	v_fma_f32 v137, v88, v137, 1.0
	v_add_f32_e32 v23, v163, v23
	v_mov_b32_e32 v149, v175
	v_exp_f32_e32 v136, v136
	v_mul_f32_e32 v137, v88, v137
	v_mul_f32_e32 v25, v22, v23
	v_mov_b32_e32 v22, v92
	v_mov_b32_e32 v23, v28
	v_mul_f32_e32 v137, 0x3fcc422a, v137
	v_pk_mul_f32 v[22:23], v[22:23], v[148:149]
	v_mov_b32_e32 v97, v175
	v_mul_f32_e32 v137, 0xbfb8aa3b, v137
	v_add_f32_e32 v23, v163, v23
	v_mov_b32_e32 v28, v93
	v_exp_f32_e32 v137, v137
	v_mul_f32_e32 v26, v22, v23
	v_pk_mul_f32 v[22:23], v[28:29], v[96:97]
	v_add_f32_e32 v134, 1.0, v136
	v_add_f32_e32 v23, v163, v23
	v_mov_b32_e32 v207, v175
	v_rcp_f32_e32 v134, v134
	v_mul_f32_e32 v27, v22, v23
	v_mov_b32_e32 v22, v86
	v_mov_b32_e32 v23, v18
	v_pk_mul_f32 v[22:23], v[22:23], v[206:207]
	v_add_f32_e32 v136, 1.0, v137
	global_store_dwordx4 v164, v[18:21], s[0:1] offset:16 sc1
	v_mov_b32_e32 v135, v175
	v_rcp_f32_e32 v136, v136
	v_add_f32_e32 v18, v163, v23
	v_mul_f32_e32 v22, v22, v18
	v_mov_b32_e32 v18, v87
	v_pk_mul_f32 v[18:19], v[18:19], v[134:135]
	v_rcp_f32_e32 v140, v139
	v_add_f32_e32 v19, v163, v19
	v_mov_b32_e32 v137, v175
	v_mul_f32_e32 v23, v18, v19
	v_mov_b32_e32 v18, v88
	v_mov_b32_e32 v19, v20
	v_pk_mul_f32 v[18:19], v[18:19], v[136:137]
	v_mov_b32_e32 v141, v175
	v_add_f32_e32 v19, v163, v19
	v_mov_b32_e32 v20, v89
	v_mul_f32_e32 v28, v18, v19
	v_pk_mul_f32 v[18:19], v[20:21], v[140:141]
	v_readlane_b32 s59, v254, 33
	v_add_f32_e32 v19, v163, v19
	v_mul_f32_e32 v21, v18, v19
	v_cvt_pk_bf16_f32 v18, v24, v25
	v_cvt_pk_bf16_f32 v19, v26, v27
	v_cvt_pk_bf16_f32 v20, v22, v23
	v_cvt_pk_bf16_f32 v21, v28, v21
	global_store_dwordx4 v[114:115], v[18:21], off offset:2048 sc1
	s_nop 1
	v_pk_mul_f32 v[18:19], v[132:133], v[138:139] op_sel_hi:[1,0]
	s_nop 0
	v_pk_fma_f32 v[10:11], v[10:11], v[18:19], v[14:15]
	v_pk_mul_f32 v[14:15], v[130:131], v[138:139] op_sel_hi:[1,0]
	s_nop 0
	v_pk_fma_f32 v[12:13], v[12:13], v[14:15], v[16:17]
	v_pk_mul_f32 v[14:15], v[84:85], v[138:139] op_sel_hi:[1,0]
	global_store_dwordx4 v162, v[10:13], s[0:1] sc1
	v_pk_fma_f32 v[2:3], v[2:3], v[14:15], v[6:7]
	v_pk_add_f32 v[14:15], v[74:75], v[78:79]
	v_pk_mul_f32 v[6:7], v[82:83], v[138:139] op_sel_hi:[1,0]
	v_mul_f32_e32 v16, 0x3d372713, v14
	v_fma_f32 v16, v14, v16, 1.0
	v_mul_f32_e32 v16, v14, v16
	v_mul_f32_e32 v16, 0x3fcc422a, v16
	v_mul_f32_e32 v16, 0xbfb8aa3b, v16
	v_exp_f32_e32 v16, v16
	v_pk_fma_f32 v[4:5], v[4:5], v[6:7], v[8:9]
	v_mov_b32_e32 v9, v10
	v_mul_f32_e32 v10, 0x3d372713, v15
	v_fma_f32 v10, v15, v10, 1.0
	v_add_f32_e32 v8, 1.0, v16
	v_mul_f32_e32 v10, v15, v10
	v_rcp_f32_e32 v164, v8
	v_mul_f32_e32 v10, 0x3fcc422a, v10
	v_mul_f32_e32 v10, 0xbfb8aa3b, v10
	v_exp_f32_e32 v10, v10
	v_mov_b32_e32 v8, v14
	s_waitcnt vmcnt(11)
	v_pk_mul_f32 v[8:9], v[8:9], v[164:165]
	v_pk_add_f32 v[6:7], v[76:77], v[80:81]
	s_waitcnt vmcnt(10)
	v_add_f32_e32 v9, v1, v9
	v_mul_f32_e32 v14, v8, v9
	v_add_f32_e32 v8, 1.0, v10
	v_rcp_f32_e32 v164, v8
	v_mul_f32_e32 v8, 0x3d372713, v6
	v_fma_f32 v8, v6, v8, 1.0
	v_mul_f32_e32 v8, v6, v8
	v_mul_f32_e32 v8, 0x3fcc422a, v8
	v_mul_f32_e32 v8, 0xbfb8aa3b, v8
	v_mov_b32_e32 v10, v15
	v_exp_f32_e32 v15, v8
	v_pk_mul_f32 v[8:9], v[10:11], v[164:165]
	global_store_dwordx4 v162, v[2:5], s[0:1] offset:16 sc1
	v_add_f32_e32 v9, v1, v9
	v_mul_f32_e32 v16, v8, v9
	v_add_f32_e32 v8, 1.0, v15
	v_rcp_f32_e32 v164, v8
	v_mul_f32_e32 v8, 0x3d372713, v7
	v_fma_f32 v8, v7, v8, 1.0
	v_mul_f32_e32 v8, v7, v8
	v_mul_f32_e32 v8, 0x3fcc422a, v8
	v_mul_f32_e32 v8, 0xbfb8aa3b, v8
	v_exp_f32_e32 v10, v8
	v_mov_b32_e32 v8, v6
	v_mov_b32_e32 v9, v12
	v_pk_mul_f32 v[8:9], v[8:9], v[164:165]
	v_add_f32_e32 v6, 1.0, v10
	v_rcp_f32_e32 v164, v6
	v_add_f32_e32 v6, v1, v9
	v_mul_f32_e32 v15, v8, v6
	v_pk_add_f32 v[8:9], v[66:67], v[70:71]
	v_mov_b32_e32 v11, v2
	v_mul_f32_e32 v10, 0x3d372713, v8
	v_fma_f32 v10, v8, v10, 1.0
	v_mul_f32_e32 v10, v8, v10
	v_mul_f32_e32 v10, 0x3fcc422a, v10
	v_mul_f32_e32 v10, 0xbfb8aa3b, v10
	v_mul_f32_e32 v2, 0x3d372713, v9
	v_exp_f32_e32 v10, v10
	v_fma_f32 v2, v9, v2, 1.0
	v_mul_f32_e32 v2, v9, v2
	v_mul_f32_e32 v2, 0x3fcc422a, v2
	v_mul_f32_e32 v2, 0xbfb8aa3b, v2
	v_mov_b32_e32 v12, v7
	v_add_f32_e32 v10, 1.0, v10
	v_exp_f32_e32 v2, v2
	v_pk_mul_f32 v[6:7], v[12:13], v[164:165]
	v_rcp_f32_e32 v164, v10
	v_add_f32_e32 v7, v1, v7
	v_mul_f32_e32 v12, v6, v7
	v_pk_add_f32 v[6:7], v[68:69], v[72:73]
	v_mov_b32_e32 v10, v8
	v_add_f32_e32 v2, 1.0, v2
	v_pk_mul_f32 v[10:11], v[10:11], v[164:165]
	v_rcp_f32_e32 v164, v2
	v_mov_b32_e32 v2, v9
	v_mul_f32_e32 v9, 0x3d372713, v6
	v_fma_f32 v9, v6, v9, 1.0
	v_mul_f32_e32 v9, v6, v9
	v_mul_f32_e32 v9, 0x3fcc422a, v9
	v_mul_f32_e32 v9, 0xbfb8aa3b, v9
	v_exp_f32_e32 v9, v9
	v_pk_mul_f32 v[2:3], v[2:3], v[164:165]
	v_add_f32_e32 v8, v1, v11
	v_add_f32_e32 v3, v1, v3
	v_mul_f32_e32 v8, v10, v8
	v_mul_f32_e32 v10, v2, v3
	v_add_f32_e32 v2, 1.0, v9
	v_rcp_f32_e32 v164, v2
	v_mul_f32_e32 v2, 0x3d372713, v7
	v_fma_f32 v2, v7, v2, 1.0
	v_mul_f32_e32 v2, v7, v2
	v_mul_f32_e32 v2, 0x3fcc422a, v2
	v_mul_f32_e32 v2, 0xbfb8aa3b, v2
	v_exp_f32_e32 v9, v2
	v_mov_b32_e32 v2, v6
	v_mov_b32_e32 v3, v4
	v_pk_mul_f32 v[2:3], v[2:3], v[164:165]
	v_add_f32_e32 v4, 1.0, v9
	v_rcp_f32_e32 v164, v4
	v_add_f32_e32 v3, v1, v3
	v_mov_b32_e32 v4, v7
	v_mul_f32_e32 v6, v2, v3
	v_pk_mul_f32 v[2:3], v[4:5], v[164:165]
	s_nop 0
	v_add_f32_e32 v1, v1, v3
	v_mul_f32_e32 v1, v2, v1
	v_cvt_pk_bf16_f32 v2, v14, v16
	v_cvt_pk_bf16_f32 v3, v15, v12
	v_cvt_pk_bf16_f32 v4, v8, v10
	v_cvt_pk_bf16_f32 v5, v6, v1
	global_store_dwordx4 v[114:115], v[2:5], off offset:3072 sc1
